# saddr DMA + first-K-iteration peel with C=0 MFMAs (no acc zeroing) in 6 GEMM loops + gates skinny GEMM with resident weights and 8-deep pipelined A loads
# speedup vs baseline: 1.0054x; 1.0054x over previous
; #define PG8_STAGE(bufoff, gbase, voff) do { _Pragma("unroll") for (int _i = 0; _i < 2; ++_i) \
;         __builtin_amdgcn_global_load_lds((const unsigned*)((const char*)(gbase) + (voff)[_i]), (LAS unsigned*)(lds + (bufoff) + ldsw + _i * 8192), 16, 0, 0); } while (0)
; #define PG8_LDA(dst, b, h) do { _Pragma("unroll") for (int m = 0; m < 4; ++m) _Pragma("unroll") for (int k = 0; k < 2; ++k) dst[m][k] = *(const LAS bf16x8*)(lds + PG8_SA(b, h) + aoff + m * 2048 + k * 1024); } while (0)
; template <class Epi, class Sched>
; __device__ __forceinline__ void gemm_phase(LAS unsigned char* lds, const int lda, const int ldb, const int K, const Sched& S, const Epi& E) {
;     ...
;     Unit cur, nxt; int ui = 0;
;     if (!S.next(0, cur)) return;
;     f32x4 acc[2][2][4][2];
; #pragma unroll
;     for (int a = 0; a < 2; ++a)
; #pragma unroll
;         for (int b = 0; b < 2; ++b)
; #pragma unroll
;             for (int m = 0; m < 4; ++m)
; #pragma unroll
;                 for (int n = 0; n < 2; ++n) acc[a][b][m][n] = (f32x4){0.f, 0.f, 0.f, 0.f};
;     bf16x8 At[4][2], B0[2][2], B1[2][2];
;     float rsv[8];
; #pragma unroll
;     for (int i = 0; i < 8; ++i) rsv[i] = 0.f;
;     const char* cA = cur.A; const char* cB = cur.B;
;     PG8_STAGE(PG8_SB(0, 0), cB, voffB); PG8_STAGE(PG8_SB(0, 1), cB + hstepB, voffB); PG8_STAGE(PG8_SA(0, 0), cA, voffA); PG8_STAGE(PG8_SA(0, 1), cA + hstepA, voffA);
;     if (wr == 1) PG8_BAR;
;     PG8_WAIT_V(2); PG8_BAR;
;     PG8_STAGE(PG8_SB(1, 0), cB + kstep, voffB); PG8_STAGE(PG8_SA(1, 0), cA + kstep, voffA); PG8_STAGE(PG8_SB(1, 1), cB + hstepB + kstep, voffB);
;     PG8_WAIT_V(6); PG8_BAR;
;     for (;;) {
;         const bool has_next = S.next(ui + 1, nxt);
;         const char* nA = has_next ? nxt.A : cA; const char* nB = has_next ? nxt.B : cB;
;         for (int t = 0; t < nt; t += 2) {
;             const bool last = (t == nt - 2);
;             const char* a1 = cA + (size_t)(t + 1) * kstep;
;             const char* a2 = last ? nA : cA + (size_t)(t + 2) * kstep; const char* b2 = last ? nB : cB + (size_t)(t + 2) * kstep;
;             const char* a3 = a2 + kstep; const char* b3 = b2 + kstep;
;             PG8_LDB(B0, 0, 0); PG8_LDB(B1, 0, 1); PG8_SCHED; PG8_LDA(At, 0, 0); PG8_STAGE(PG8_SA(1, 1), a1 + hstepA, voffA);
;             PG8_WAIT_V(8); PG8_WAIT_L(0); PG8_BAR; PG8_MMA(0, 0, At, B0); PG8_MMA(0, 1, At, B1); PG8_BAR; PG8_SCHED;
.LBB0_240:
	s_lshl_b32 s20, s20, 8
	s_ashr_i32 s21, s20, 31
	s_add_u32 s22, s22, 0x40080
	s_addc_u32 s23, s23, 0
	s_add_u32 s13, s24, 0x100
	s_addc_u32 s15, s25, 0
	s_mov_b32 s65, -2
	v_lshl_add_u64 v[214:215], s[20:21], 2, v[204:205]
	v_add_u32_e32 v230, 0x80, v200
	v_add_u32_e32 v231, 0x80, v196
	v_add_u32_e32 v232, 0x80, v202
	v_add_u32_e32 v233, 0x80, v198
	s_add_u32 s21, s22, 0xfffc0080
	s_addc_u32 s24, s23, -1
	s_cmp_eq_u32 s65, 12
	s_cselect_b32 s29, s17, s24
	s_cselect_b32 s28, s16, s21
	s_cselect_b32 s31, s19, s15
	s_cselect_b32 s30, s18, s13
	s_add_i32 s72, s50, s3
	ds_read_b128 v[130:133], v217
	ds_read_b128 v[134:137], v217 offset:1024
	ds_read_b128 v[138:141], v217 offset:2048
	ds_read_b128 v[142:145], v217 offset:3072
	ds_read_b128 v[146:149], v218
	ds_read_b128 v[150:153], v218 offset:1024
	ds_read_b128 v[154:157], v218 offset:2048
	ds_read_b128 v[158:161], v218 offset:3072
	s_add_i32 m0, s37, 0xc000
	s_add_i32 s71, s37, 0xe000
	s_add_i32 s73, s72, 0x2000
	s_add_u32 s48, s30, 0x40000
	s_addc_u32 s49, s31, 0
	s_add_i32 s74, s51, s3
	s_add_i32 s75, s74, 0x2000
	s_add_i32 s76, 0, 0x18000
	s_add_i32 s77, 0, 0x1c000
	s_add_u32 s26, s28, 0x40000
	s_addc_u32 s27, s29, 0
	s_add_i32 s68, s76, s3
	s_add_i32 s21, s68, 0x2000
	s_add_u32 s24, s30, 0x40080
	s_addc_u32 s25, s31, 0
	s_add_i32 s70, s77, s3
	s_add_i32 s69, s70, 0x2000
	s_cmp_lg_u32 s65, 12
	ds_read_b128 v[162:165], v219
	ds_read_b128 v[166:169], v219 offset:1024
	ds_read_b128 v[170:173], v219 offset:2048
	ds_read_b128 v[174:177], v219 offset:3072
	ds_read_b128 v[178:181], v219 offset:4096
	ds_read_b128 v[182:185], v219 offset:5120
	ds_read_b128 v[186:189], v219 offset:6144
	ds_read_b128 v[190:193], v219 offset:7168
	global_load_lds_dwordx4 v206, s[22:23]
	s_mov_b32 m0, s71
	s_nop 0
	global_load_lds_dwordx4 v208, s[22:23]
	s_waitcnt vmcnt(8)
	s_waitcnt lgkmcnt(0)
	s_barrier
	s_setprio 1
	s_waitcnt lgkmcnt(0)
	v_mfma_f32_16x16x32_bf16 v[126:129], v[130:133], v[162:165], 0
	v_mfma_f32_16x16x32_bf16 v[118:121], v[138:141], v[162:165], 0
	v_mfma_f32_16x16x32_bf16 v[110:113], v[130:133], v[170:173], 0
	v_mfma_f32_16x16x32_bf16 v[102:105], v[138:141], v[170:173], 0
	v_mfma_f32_16x16x32_bf16 v[94:97], v[130:133], v[178:181], 0
	v_mfma_f32_16x16x32_bf16 v[86:89], v[138:141], v[178:181], 0
	v_mfma_f32_16x16x32_bf16 v[78:81], v[130:133], v[186:189], 0
	v_mfma_f32_16x16x32_bf16 v[70:73], v[138:141], v[186:189], 0
	v_mfma_f32_16x16x32_bf16 v[126:129], v[134:137], v[166:169], v[126:129]
	v_mfma_f32_16x16x32_bf16 v[118:121], v[142:145], v[166:169], v[118:121]
	v_mfma_f32_16x16x32_bf16 v[110:113], v[134:137], v[174:177], v[110:113]
	v_mfma_f32_16x16x32_bf16 v[102:105], v[142:145], v[174:177], v[102:105]
	v_mfma_f32_16x16x32_bf16 v[94:97], v[134:137], v[182:185], v[94:97]
	v_mfma_f32_16x16x32_bf16 v[86:89], v[142:145], v[182:185], v[86:89]
	v_mfma_f32_16x16x32_bf16 v[78:81], v[134:137], v[190:193], v[78:81]
	v_mfma_f32_16x16x32_bf16 v[70:73], v[142:145], v[190:193], v[70:73]
	s_setprio 0
	s_setprio 1
	v_mfma_f32_16x16x32_bf16 v[122:125], v[146:149], v[162:165], 0
	v_mfma_f32_16x16x32_bf16 v[114:117], v[154:157], v[162:165], 0
	v_mfma_f32_16x16x32_bf16 v[106:109], v[146:149], v[170:173], 0
	v_mfma_f32_16x16x32_bf16 v[98:101], v[154:157], v[170:173], 0
	v_mfma_f32_16x16x32_bf16 v[90:93], v[146:149], v[178:181], 0
	v_mfma_f32_16x16x32_bf16 v[82:85], v[154:157], v[178:181], 0
	v_mfma_f32_16x16x32_bf16 v[74:77], v[146:149], v[186:189], 0
	v_mfma_f32_16x16x32_bf16 v[66:69], v[154:157], v[186:189], 0
	v_mfma_f32_16x16x32_bf16 v[122:125], v[150:153], v[166:169], v[122:125]
	v_mfma_f32_16x16x32_bf16 v[114:117], v[158:161], v[166:169], v[114:117]
	v_mfma_f32_16x16x32_bf16 v[106:109], v[150:153], v[174:177], v[106:109]
	v_mfma_f32_16x16x32_bf16 v[98:101], v[158:161], v[174:177], v[98:101]
	v_mfma_f32_16x16x32_bf16 v[90:93], v[150:153], v[182:185], v[90:93]
	v_mfma_f32_16x16x32_bf16 v[82:85], v[158:161], v[182:185], v[82:85]
	v_mfma_f32_16x16x32_bf16 v[74:77], v[150:153], v[190:193], v[74:77]
	v_mfma_f32_16x16x32_bf16 v[66:69], v[158:161], v[190:193], v[66:69]
	s_setprio 0
	s_barrier
; #define PG8_STAGE(bufoff, gbase, voff) do { _Pragma("unroll") for (int _i = 0; _i < 2; ++_i) \
;         __builtin_amdgcn_global_load_lds((const unsigned*)((const char*)(gbase) + (voff)[_i]), (LAS unsigned*)(lds + (bufoff) + ldsw + _i * 8192), 16, 0, 0); } while (0)
; #define PG8_LDA(dst, b, h) do { _Pragma("unroll") for (int m = 0; m < 4; ++m) _Pragma("unroll") for (int k = 0; k < 2; ++k) dst[m][k] = *(const LAS bf16x8*)(lds + PG8_SA(b, h) + aoff + m * 2048 + k * 1024); } while (0)
; #define PG8_MMA(ai, bj, At, Bt) do { __builtin_amdgcn_s_setprio(1); _Pragma("unroll") for (int m = 0; m < 4; ++m) _Pragma("unroll") for (int n = 0; n < 2; ++n) _Pragma("unroll") for (int k = 0; k < 2; ++k) \
;         acc[ai][bj][m][n] = __builtin_amdgcn_mfma_f32_16x16x32_bf16(Bt[n][k], At[m][k], acc[ai][bj][m][n], 0, 0, 0); __builtin_amdgcn_s_setprio(0); } while (0)
; #define PG8_WAIT_V(n) asm volatile("s_waitcnt vmcnt(" #n ")" ::: "memory")
; #define PG8_WAIT_L(n) asm volatile("s_waitcnt lgkmcnt(" #n ")" ::: "memory")
; #define PG8_BAR __builtin_amdgcn_s_barrier()
; #define PG8_SCHED __builtin_amdgcn_sched_barrier(0)
; template <class Epi, class Sched>
; __device__ __forceinline__ void gemm_phase(LAS unsigned char* lds, const int lda, const int ldb, const int K, const Sched& S, const Epi& E) {
;     ...
;             PG8_LDA(At, 0, 1); PG8_STAGE(PG8_SB(0, 0), b2, voffB); PG8_STAGE(PG8_SB(0, 1), b2 + hstepB, voffB); PG8_STAGE(PG8_SA(0, 0), a2, voffA);
;             PG8_WAIT_V(8); PG8_WAIT_L(0); PG8_BAR; PG8_MMA(1, 0, At, B0); PG8_MMA(1, 1, At, B1); PG8_BAR; PG8_SCHED;
	s_mov_b32 m0, s72
	ds_read_b128 v[162:165], v219 offset:16384
	ds_read_b128 v[166:169], v219 offset:17408
	ds_read_b128 v[170:173], v219 offset:18432
	ds_read_b128 v[174:177], v219 offset:19456
	ds_read_b128 v[178:181], v219 offset:20480
	ds_read_b128 v[182:185], v219 offset:21504
	ds_read_b128 v[186:189], v219 offset:22528
	ds_read_b128 v[190:193], v219 offset:23552
	global_load_lds_dwordx4 v200, s[30:31]
	s_mov_b32 m0, s73
	s_nop 0
	global_load_lds_dwordx4 v196, s[30:31]
	s_mov_b32 m0, s74
	s_nop 0
	global_load_lds_dwordx4 v200, s[48:49]
	s_mov_b32 m0, s75
	s_nop 0
	global_load_lds_dwordx4 v196, s[48:49]
	s_mov_b32 m0, s37
	s_nop 0
	global_load_lds_dwordx4 v202, s[28:29]
	s_mov_b32 m0, s38
	s_nop 0
	global_load_lds_dwordx4 v198, s[28:29]
	s_waitcnt vmcnt(8)
	s_waitcnt lgkmcnt(0)
	s_barrier
	s_setprio 1
	s_waitcnt lgkmcnt(0)
	v_mfma_f32_16x16x32_bf16 v[62:65], v[130:133], v[162:165], 0
	v_mfma_f32_16x16x32_bf16 v[54:57], v[138:141], v[162:165], 0
	v_mfma_f32_16x16x32_bf16 v[46:49], v[130:133], v[170:173], 0
	v_mfma_f32_16x16x32_bf16 v[38:41], v[138:141], v[170:173], 0
	v_mfma_f32_16x16x32_bf16 v[30:33], v[130:133], v[178:181], 0
	v_mfma_f32_16x16x32_bf16 v[22:25], v[138:141], v[178:181], 0
	v_mfma_f32_16x16x32_bf16 v[14:17], v[130:133], v[186:189], 0
	v_mfma_f32_16x16x32_bf16 v[6:9], v[138:141], v[186:189], 0
	v_mfma_f32_16x16x32_bf16 v[62:65], v[134:137], v[166:169], v[62:65]
	v_mfma_f32_16x16x32_bf16 v[54:57], v[142:145], v[166:169], v[54:57]
	v_mfma_f32_16x16x32_bf16 v[46:49], v[134:137], v[174:177], v[46:49]
	v_mfma_f32_16x16x32_bf16 v[38:41], v[142:145], v[174:177], v[38:41]
	v_mfma_f32_16x16x32_bf16 v[30:33], v[134:137], v[182:185], v[30:33]
	v_mfma_f32_16x16x32_bf16 v[22:25], v[142:145], v[182:185], v[22:25]
	v_mfma_f32_16x16x32_bf16 v[14:17], v[134:137], v[190:193], v[14:17]
	v_mfma_f32_16x16x32_bf16 v[6:9], v[142:145], v[190:193], v[6:9]
	s_setprio 0
	s_setprio 1
	v_mfma_f32_16x16x32_bf16 v[58:61], v[146:149], v[162:165], 0
	v_mfma_f32_16x16x32_bf16 v[50:53], v[154:157], v[162:165], 0
	v_mfma_f32_16x16x32_bf16 v[42:45], v[146:149], v[170:173], 0
	v_mfma_f32_16x16x32_bf16 v[34:37], v[154:157], v[170:173], 0
	v_mfma_f32_16x16x32_bf16 v[26:29], v[146:149], v[178:181], 0
	v_mfma_f32_16x16x32_bf16 v[18:21], v[154:157], v[178:181], 0
	v_mfma_f32_16x16x32_bf16 v[10:13], v[146:149], v[186:189], 0
	v_mfma_f32_16x16x32_bf16 v[2:5], v[154:157], v[186:189], 0
	v_mfma_f32_16x16x32_bf16 v[58:61], v[150:153], v[166:169], v[58:61]
	v_mfma_f32_16x16x32_bf16 v[50:53], v[158:161], v[166:169], v[50:53]
	v_mfma_f32_16x16x32_bf16 v[42:45], v[150:153], v[174:177], v[42:45]
	v_mfma_f32_16x16x32_bf16 v[34:37], v[158:161], v[174:177], v[34:37]
	v_mfma_f32_16x16x32_bf16 v[26:29], v[150:153], v[182:185], v[26:29]
	v_mfma_f32_16x16x32_bf16 v[18:21], v[158:161], v[182:185], v[18:21]
	v_mfma_f32_16x16x32_bf16 v[10:13], v[150:153], v[190:193], v[10:13]
	v_mfma_f32_16x16x32_bf16 v[2:5], v[158:161], v[190:193], v[2:5]
	s_setprio 0
	s_barrier
	s_branch .Lpeel1_join

; #define PG8_STAGE(bufoff, gbase, voff) do { _Pragma("unroll") for (int _i = 0; _i < 2; ++_i) \
;         __builtin_amdgcn_global_load_lds((const unsigned*)((const char*)(gbase) + (voff)[_i]), (LAS unsigned*)(lds + (bufoff) + ldsw + _i * 8192), 16, 0, 0); } while (0)
; #define PG8_LDA(dst, b, h) do { _Pragma("unroll") for (int m = 0; m < 4; ++m) _Pragma("unroll") for (int k = 0; k < 2; ++k) dst[m][k] = *(const LAS bf16x8*)(lds + PG8_SA(b, h) + aoff + m * 2048 + k * 1024); } while (0)
; #define PG8_LDB(dst, b, h) do { _Pragma("unroll") for (int n = 0; n < 2; ++n) _Pragma("unroll") for (int k = 0; k < 2; ++k) dst[n][k] = *(const LAS bf16x8*)(lds + PG8_SB(b, h) + boff + n * 2048 + k * 1024); } while (0)
; #define PG8_MMA(ai, bj, At, Bt) do { __builtin_amdgcn_s_setprio(1); _Pragma("unroll") for (int m = 0; m < 4; ++m) _Pragma("unroll") for (int n = 0; n < 2; ++n) _Pragma("unroll") for (int k = 0; k < 2; ++k) \
;         acc[ai][bj][m][n] = __builtin_amdgcn_mfma_f32_16x16x32_bf16(Bt[n][k], At[m][k], acc[ai][bj][m][n], 0, 0, 0); __builtin_amdgcn_s_setprio(0); } while (0)
; #define PG8_WAIT_V(n) asm volatile("s_waitcnt vmcnt(" #n ")" ::: "memory")
; #define PG8_WAIT_L(n) asm volatile("s_waitcnt lgkmcnt(" #n ")" ::: "memory")
; #define PG8_BAR __builtin_amdgcn_s_barrier()
; #define PG8_SCHED __builtin_amdgcn_sched_barrier(0)
; template <class Epi, class Sched>
; __device__ __forceinline__ void gemm_phase(LAS unsigned char* lds, const int lda, const int ldb, const int K, const Sched& S, const Epi& E) {
;     ...
;             PG8_LDB(B0, 1, 0); PG8_LDB(B1, 1, 1); PG8_SCHED; PG8_LDA(At, 1, 0); PG8_STAGE(PG8_SA(0, 1), a2 + hstepA, voffA);
;             PG8_WAIT_V(8); PG8_WAIT_L(0); PG8_BAR; PG8_MMA(0, 0, At, B0); PG8_MMA(0, 1, At, B1); PG8_BAR; PG8_SCHED;
;             PG8_LDA(At, 1, 1); PG8_STAGE(PG8_SB(1, 0), b3, voffB); PG8_STAGE(PG8_SB(1, 1), b3 + hstepB, voffB); PG8_STAGE(PG8_SA(1, 0), a3, voffA);
;             PG8_WAIT_V(8); PG8_WAIT_L(0); PG8_BAR;
;             if (last) E.pre(cur, wr, fr, rsv);
;     __device__ __forceinline__ void pre(const pg8::Unit& u, int wr, int fr, float (&rsv)[8]) const {
;         const float* p = ss + u.pm * 256 + wr * 64 + fr;
; #pragma unroll
;         for (int ai = 0; ai < 2; ++ai)
; #pragma unroll
;             for (int m = 0; m < 4; ++m) rsv[ai * 4 + m] = p[ai * 128 + m * 16];
;     }
.Lpeel1_join:
	v_add_u32_e32 v130, s76, v195
	v_add_u32_e32 v142, s77, v195
	ds_read_b128 v[146:149], v130
	ds_read_b128 v[150:153], v130 offset:1024
	ds_read_b128 v[154:157], v130 offset:2048
	ds_read_b128 v[158:161], v130 offset:3072
	ds_read_b128 v[130:133], v142
	ds_read_b128 v[134:137], v142 offset:1024
	ds_read_b128 v[138:141], v142 offset:2048
	ds_read_b128 v[142:145], v142 offset:3072
	s_mov_b32 m0, s39
	ds_read_b128 v[162:165], v219 offset:32768
	ds_read_b128 v[166:169], v219 offset:33792
	ds_read_b128 v[170:173], v219 offset:34816
	ds_read_b128 v[174:177], v219 offset:35840
	ds_read_b128 v[178:181], v219 offset:36864
	ds_read_b128 v[182:185], v219 offset:37888
	ds_read_b128 v[186:189], v219 offset:38912
	ds_read_b128 v[190:193], v219 offset:39936
	global_load_lds_dwordx4 v202, s[26:27]
	s_mov_b32 m0, s40
	s_nop 0
	global_load_lds_dwordx4 v198, s[26:27]
	s_waitcnt vmcnt(8)
	s_waitcnt lgkmcnt(0)
	s_barrier
	s_setprio 1
	s_waitcnt lgkmcnt(0)
	v_mfma_f32_16x16x32_bf16 v[126:129], v[146:149], v[162:165], v[126:129]
	v_mfma_f32_16x16x32_bf16 v[118:121], v[154:157], v[162:165], v[118:121]
	v_mfma_f32_16x16x32_bf16 v[110:113], v[146:149], v[170:173], v[110:113]
	v_mfma_f32_16x16x32_bf16 v[102:105], v[154:157], v[170:173], v[102:105]
	v_mfma_f32_16x16x32_bf16 v[94:97], v[146:149], v[178:181], v[94:97]
	v_mfma_f32_16x16x32_bf16 v[86:89], v[154:157], v[178:181], v[86:89]
	v_mfma_f32_16x16x32_bf16 v[78:81], v[146:149], v[186:189], v[78:81]
	v_mfma_f32_16x16x32_bf16 v[70:73], v[154:157], v[186:189], v[70:73]
	v_mfma_f32_16x16x32_bf16 v[126:129], v[150:153], v[166:169], v[126:129]
	v_mfma_f32_16x16x32_bf16 v[118:121], v[158:161], v[166:169], v[118:121]
	v_mfma_f32_16x16x32_bf16 v[110:113], v[150:153], v[174:177], v[110:113]
	v_mfma_f32_16x16x32_bf16 v[102:105], v[158:161], v[174:177], v[102:105]
	v_mfma_f32_16x16x32_bf16 v[94:97], v[150:153], v[182:185], v[94:97]
	v_mfma_f32_16x16x32_bf16 v[86:89], v[158:161], v[182:185], v[86:89]
	v_mfma_f32_16x16x32_bf16 v[78:81], v[150:153], v[190:193], v[78:81]
	v_mfma_f32_16x16x32_bf16 v[70:73], v[158:161], v[190:193], v[70:73]
	s_setprio 0
	s_setprio 1
	v_mfma_f32_16x16x32_bf16 v[122:125], v[130:133], v[162:165], v[122:125]
	v_mfma_f32_16x16x32_bf16 v[114:117], v[138:141], v[162:165], v[114:117]
	v_mfma_f32_16x16x32_bf16 v[106:109], v[130:133], v[170:173], v[106:109]
	v_mfma_f32_16x16x32_bf16 v[98:101], v[138:141], v[170:173], v[98:101]
	v_mfma_f32_16x16x32_bf16 v[90:93], v[130:133], v[178:181], v[90:93]
	v_mfma_f32_16x16x32_bf16 v[82:85], v[138:141], v[178:181], v[82:85]
	v_mfma_f32_16x16x32_bf16 v[74:77], v[130:133], v[186:189], v[74:77]
	v_mfma_f32_16x16x32_bf16 v[66:69], v[138:141], v[186:189], v[66:69]
	v_mfma_f32_16x16x32_bf16 v[122:125], v[134:137], v[166:169], v[122:125]
	v_mfma_f32_16x16x32_bf16 v[114:117], v[142:145], v[166:169], v[114:117]
	v_mfma_f32_16x16x32_bf16 v[106:109], v[134:137], v[174:177], v[106:109]
	v_mfma_f32_16x16x32_bf16 v[98:101], v[142:145], v[174:177], v[98:101]
	v_mfma_f32_16x16x32_bf16 v[90:93], v[134:137], v[182:185], v[90:93]
	v_mfma_f32_16x16x32_bf16 v[82:85], v[142:145], v[182:185], v[82:85]
	v_mfma_f32_16x16x32_bf16 v[74:77], v[134:137], v[190:193], v[74:77]
	v_mfma_f32_16x16x32_bf16 v[66:69], v[142:145], v[190:193], v[66:69]
	s_setprio 0
	s_barrier
	s_mov_b32 m0, s68
	ds_read_b128 v[186:189], v219 offset:49152
	ds_read_b128 v[190:193], v219 offset:50176
	ds_read_b128 v[178:181], v219 offset:51200
	ds_read_b128 v[182:185], v219 offset:52224
	ds_read_b128 v[170:173], v219 offset:53248
	ds_read_b128 v[174:177], v219 offset:54272
	ds_read_b128 v[162:165], v219 offset:55296
	ds_read_b128 v[166:169], v219 offset:56320
	global_load_lds_dwordx4 v230, s[30:31]
	s_mov_b32 m0, s21
	s_nop 0
	global_load_lds_dwordx4 v231, s[30:31]
	s_mov_b32 m0, s70
	s_nop 0
	global_load_lds_dwordx4 v200, s[24:25]
	s_mov_b32 m0, s69
	s_nop 0
	global_load_lds_dwordx4 v196, s[24:25]
	s_mov_b32 m0, s42
	s_nop 0
	global_load_lds_dwordx4 v232, s[28:29]
	s_mov_b32 m0, s43
	s_nop 0
	global_load_lds_dwordx4 v233, s[28:29]
	s_waitcnt vmcnt(8)
	s_waitcnt lgkmcnt(0)
	s_barrier
	s_cbranch_scc1 .LBB0_241
	global_load_dword v228, v[214:215], off
	global_load_dword v227, v[214:215], off offset:64
	global_load_dword v226, v[214:215], off offset:128
	global_load_dword v225, v[214:215], off offset:192
	global_load_dword v224, v[214:215], off offset:512
	global_load_dword v223, v[214:215], off offset:576
	global_load_dword v222, v[214:215], off offset:640
	global_load_dword v221, v[214:215], off offset:704
	s_branch .LBB0_241

; #define PG8_LDA(dst, b, h) do { _Pragma("unroll") for (int m = 0; m < 4; ++m) _Pragma("unroll") for (int k = 0; k < 2; ++k) dst[m][k] = *(const LAS bf16x8*)(lds + PG8_SA(b, h) + aoff + m * 2048 + k * 1024); } while (0)
; template <class Epi, class Sched>
; __device__ __forceinline__ void gemm_phase(LAS unsigned char* lds, const int lda, const int ldb, const int K, const Sched& S, const Epi& E) {
;     ...
;     Unit cur, nxt; int ui = 0;
;     if (!S.next(0, cur)) return;
;     f32x4 acc[2][2][4][2];
; #pragma unroll
;     for (int a = 0; a < 2; ++a)
; #pragma unroll
;         for (int b = 0; b < 2; ++b)
; #pragma unroll
;             for (int m = 0; m < 4; ++m)
; #pragma unroll
;                 for (int n = 0; n < 2; ++n) acc[a][b][m][n] = (f32x4){0.f, 0.f, 0.f, 0.f};
;     bf16x8 At[4][2], B0[2][2], B1[2][2];
;     float rsv[8];
; #pragma unroll
;     for (int i = 0; i < 8; ++i) rsv[i] = 0.f;
;     const char* cA = cur.A; const char* cB = cur.B;
;     PG8_STAGE(PG8_SB(0, 0), cB, voffB); PG8_STAGE(PG8_SB(0, 1), cB + hstepB, voffB); PG8_STAGE(PG8_SA(0, 0), cA, voffA); PG8_STAGE(PG8_SA(0, 1), cA + hstepA, voffA);
;     if (wr == 1) PG8_BAR;
;     PG8_WAIT_V(2); PG8_BAR;
;     PG8_STAGE(PG8_SB(1, 0), cB + kstep, voffB); PG8_STAGE(PG8_SA(1, 0), cA + kstep, voffA); PG8_STAGE(PG8_SB(1, 1), cB + hstepB + kstep, voffB);
;     PG8_WAIT_V(6); PG8_BAR;
;     for (;;) {
;         const bool has_next = S.next(ui + 1, nxt);
;         const char* nA = has_next ? nxt.A : cA; const char* nB = has_next ? nxt.B : cB;
;         for (int t = 0; t < nt; t += 2) {
;             const bool last = (t == nt - 2);
;             const char* a1 = cA + (size_t)(t + 1) * kstep;
;             const char* a2 = last ? nA : cA + (size_t)(t + 2) * kstep; const char* b2 = last ? nB : cB + (size_t)(t + 2) * kstep;
;             const char* a3 = a2 + kstep; const char* b3 = b2 + kstep;
;             PG8_LDB(B0, 0, 0); PG8_LDB(B1, 0, 1); PG8_SCHED; PG8_LDA(At, 0, 0); PG8_STAGE(PG8_SA(1, 1), a1 + hstepA, voffA);
;             PG8_WAIT_V(8); PG8_WAIT_L(0); PG8_BAR; PG8_MMA(0, 0, At, B0); PG8_MMA(0, 1, At, B1); PG8_BAR; PG8_SCHED;
;             PG8_LDA(At, 0, 1); PG8_STAGE(PG8_SB(0, 0), b2, voffB); PG8_STAGE(PG8_SB(0, 1), b2 + hstepB, voffB); PG8_STAGE(PG8_SA(0, 0), a2, voffA);
;             PG8_WAIT_V(8); PG8_WAIT_L(0); PG8_BAR; PG8_MMA(1, 0, At, B0); PG8_MMA(1, 1, At, B1); PG8_BAR; PG8_SCHED;
.LBB0_325:
	s_add_u32 s18, s18, 0xb0080
	s_addc_u32 s19, s19, 0
	s_add_u32 s48, s20, 0x100
	s_addc_u32 s49, s21, 0
	s_mov_b32 s50, -2
	s_waitcnt lgkmcnt(0)
	v_add_u32_e32 v192, 0x80, v156
	v_add_u32_e32 v193, 0x80, v160
	v_add_u32_e32 v220, 0x80, v154
	v_add_u32_e32 v221, 0x80, v158
	ds_read_b128 v[130:133], v188
	ds_read_b128 v[134:137], v188 offset:1024
	ds_read_b128 v[138:141], v188 offset:2048
	ds_read_b128 v[142:145], v188 offset:3072
	ds_read_b128 v[146:149], v189
	ds_read_b128 v[150:153], v189 offset:1024
	ds_read_b128 v[170:173], v189 offset:2048
	ds_read_b128 v[174:177], v189 offset:3072
	s_add_u32 s20, s18, 0xfff50080
	s_addc_u32 s21, s19, -1
	s_cmp_eq_u32 s50, 40
	s_cselect_b32 s23, s15, s21
	s_cselect_b32 s22, s14, s20
	s_cselect_b32 s21, s17, s49
	s_cselect_b32 s20, s16, s48
	s_add_i32 m0, s26, 0xc000
	ds_read_b128 v[178:181], v190
	ds_read_b128 v[182:185], v190 offset:1024
	ds_read_b128 v[196:199], v190 offset:2048
	ds_read_b128 v[200:203], v190 offset:3072
	ds_read_b128 v[204:207], v190 offset:4096
	ds_read_b128 v[208:211], v190 offset:5120
	ds_read_b128 v[212:215], v190 offset:6144
	ds_read_b128 v[216:219], v190 offset:7168
	global_load_lds_dwordx4 v162, s[18:19]
	s_add_i32 m0, s26, 0xe000
	s_nop 0
	global_load_lds_dwordx4 v164, s[18:19]
	s_waitcnt vmcnt(8)
	s_waitcnt lgkmcnt(0)
	s_barrier
	s_setprio 1
	s_waitcnt lgkmcnt(0)
	v_mfma_f32_16x16x32_bf16 v[126:129], v[130:133], v[178:181], 0
	v_mfma_f32_16x16x32_bf16 v[122:125], v[138:141], v[178:181], 0
	v_mfma_f32_16x16x32_bf16 v[110:113], v[130:133], v[196:199], 0
	v_mfma_f32_16x16x32_bf16 v[106:109], v[138:141], v[196:199], 0
	v_mfma_f32_16x16x32_bf16 v[94:97], v[130:133], v[204:207], 0
	v_mfma_f32_16x16x32_bf16 v[90:93], v[138:141], v[204:207], 0
	v_mfma_f32_16x16x32_bf16 v[78:81], v[130:133], v[212:215], 0
	v_mfma_f32_16x16x32_bf16 v[74:77], v[138:141], v[212:215], 0
	v_mfma_f32_16x16x32_bf16 v[126:129], v[134:137], v[182:185], v[126:129]
	v_mfma_f32_16x16x32_bf16 v[122:125], v[142:145], v[182:185], v[122:125]
	v_mfma_f32_16x16x32_bf16 v[110:113], v[134:137], v[200:203], v[110:113]
	v_mfma_f32_16x16x32_bf16 v[106:109], v[142:145], v[200:203], v[106:109]
	v_mfma_f32_16x16x32_bf16 v[94:97], v[134:137], v[208:211], v[94:97]
	v_mfma_f32_16x16x32_bf16 v[90:93], v[142:145], v[208:211], v[90:93]
	v_mfma_f32_16x16x32_bf16 v[78:81], v[134:137], v[216:219], v[78:81]
	v_mfma_f32_16x16x32_bf16 v[74:77], v[142:145], v[216:219], v[74:77]
	s_setprio 0
	s_setprio 1
	v_mfma_f32_16x16x32_bf16 v[118:121], v[146:149], v[178:181], 0
	v_mfma_f32_16x16x32_bf16 v[114:117], v[170:173], v[178:181], 0
	v_mfma_f32_16x16x32_bf16 v[102:105], v[146:149], v[196:199], 0
	v_mfma_f32_16x16x32_bf16 v[98:101], v[170:173], v[196:199], 0
	v_mfma_f32_16x16x32_bf16 v[86:89], v[146:149], v[204:207], 0
	v_mfma_f32_16x16x32_bf16 v[82:85], v[170:173], v[204:207], 0
	v_mfma_f32_16x16x32_bf16 v[70:73], v[146:149], v[212:215], 0
	v_mfma_f32_16x16x32_bf16 v[66:69], v[170:173], v[212:215], 0
	v_mfma_f32_16x16x32_bf16 v[118:121], v[150:153], v[182:185], v[118:121]
	v_mfma_f32_16x16x32_bf16 v[114:117], v[174:177], v[182:185], v[114:117]
	v_mfma_f32_16x16x32_bf16 v[102:105], v[150:153], v[200:203], v[102:105]
	v_mfma_f32_16x16x32_bf16 v[98:101], v[174:177], v[200:203], v[98:101]
	v_mfma_f32_16x16x32_bf16 v[86:89], v[150:153], v[208:211], v[86:89]
	v_mfma_f32_16x16x32_bf16 v[82:85], v[174:177], v[208:211], v[82:85]
	v_mfma_f32_16x16x32_bf16 v[70:73], v[150:153], v[216:219], v[70:73]
	v_mfma_f32_16x16x32_bf16 v[66:69], v[174:177], v[216:219], v[66:69]
	s_setprio 0
	s_barrier
	s_add_i32 s51, s40, s25
	s_mov_b32 m0, s51
	ds_read_b128 v[178:181], v190 offset:16384
	ds_read_b128 v[182:185], v190 offset:17408
	ds_read_b128 v[196:199], v190 offset:18432
	ds_read_b128 v[200:203], v190 offset:19456
	ds_read_b128 v[204:207], v190 offset:20480
	ds_read_b128 v[208:211], v190 offset:21504
	ds_read_b128 v[212:215], v190 offset:22528
	ds_read_b128 v[216:219], v190 offset:23552
	global_load_lds_dwordx4 v156, s[20:21]
	s_add_i32 m0, s51, 0x2000
	s_add_u32 s62, s20, 0xb0000
	s_mov_b64 s[98:99], s[20:21]
	s_addc_u32 s63, s21, 0
	s_add_i32 s51, s41, s25
	global_load_lds_dwordx4 v160, s[20:21]
	s_mov_b32 m0, s51
	s_mov_b64 s[100:101], s[22:23]
	global_load_lds_dwordx4 v156, s[62:63]
	s_add_i32 m0, s51, 0x2000
	s_nop 0
	global_load_lds_dwordx4 v160, s[62:63]
	s_mov_b32 m0, s26
	s_nop 0
	global_load_lds_dwordx4 v154, s[22:23]
	s_mov_b32 m0, s27
	s_nop 0
	global_load_lds_dwordx4 v158, s[22:23]
	s_waitcnt vmcnt(8)
	s_waitcnt lgkmcnt(0)
	s_barrier
	s_setprio 1
	s_waitcnt lgkmcnt(0)
	v_mfma_f32_16x16x32_bf16 v[62:65], v[130:133], v[178:181], 0
	v_mfma_f32_16x16x32_bf16 v[58:61], v[138:141], v[178:181], 0
	v_mfma_f32_16x16x32_bf16 v[46:49], v[130:133], v[196:199], 0
	v_mfma_f32_16x16x32_bf16 v[42:45], v[138:141], v[196:199], 0
	v_mfma_f32_16x16x32_bf16 v[30:33], v[130:133], v[204:207], 0
	v_mfma_f32_16x16x32_bf16 v[26:29], v[138:141], v[204:207], 0
	v_mfma_f32_16x16x32_bf16 v[14:17], v[130:133], v[212:215], 0
	v_mfma_f32_16x16x32_bf16 v[10:13], v[138:141], v[212:215], 0
	v_mfma_f32_16x16x32_bf16 v[62:65], v[134:137], v[182:185], v[62:65]
	v_mfma_f32_16x16x32_bf16 v[58:61], v[142:145], v[182:185], v[58:61]
	v_mfma_f32_16x16x32_bf16 v[46:49], v[134:137], v[200:203], v[46:49]
	v_mfma_f32_16x16x32_bf16 v[42:45], v[142:145], v[200:203], v[42:45]
	v_mfma_f32_16x16x32_bf16 v[30:33], v[134:137], v[208:211], v[30:33]
	v_mfma_f32_16x16x32_bf16 v[26:29], v[142:145], v[208:211], v[26:29]
	v_mfma_f32_16x16x32_bf16 v[14:17], v[134:137], v[216:219], v[14:17]
	v_mfma_f32_16x16x32_bf16 v[10:13], v[142:145], v[216:219], v[10:13]
	s_setprio 0
	s_setprio 1
	v_mfma_f32_16x16x32_bf16 v[54:57], v[146:149], v[178:181], 0
	v_mfma_f32_16x16x32_bf16 v[50:53], v[170:173], v[178:181], 0
	v_mfma_f32_16x16x32_bf16 v[38:41], v[146:149], v[196:199], 0
	v_mfma_f32_16x16x32_bf16 v[34:37], v[170:173], v[196:199], 0
	v_mfma_f32_16x16x32_bf16 v[22:25], v[146:149], v[204:207], 0
	v_mfma_f32_16x16x32_bf16 v[18:21], v[170:173], v[204:207], 0
	v_mfma_f32_16x16x32_bf16 v[6:9], v[146:149], v[212:215], 0
	v_mfma_f32_16x16x32_bf16 v[2:5], v[170:173], v[212:215], 0
	v_mfma_f32_16x16x32_bf16 v[54:57], v[150:153], v[182:185], v[54:57]
	v_mfma_f32_16x16x32_bf16 v[50:53], v[174:177], v[182:185], v[50:53]
	v_mfma_f32_16x16x32_bf16 v[38:41], v[150:153], v[200:203], v[38:41]
	v_mfma_f32_16x16x32_bf16 v[34:37], v[174:177], v[200:203], v[34:37]
	v_mfma_f32_16x16x32_bf16 v[22:25], v[150:153], v[208:211], v[22:25]
	v_mfma_f32_16x16x32_bf16 v[18:21], v[174:177], v[208:211], v[18:21]
	v_mfma_f32_16x16x32_bf16 v[6:9], v[150:153], v[216:219], v[6:9]
	v_mfma_f32_16x16x32_bf16 v[2:5], v[174:177], v[216:219], v[2:5]
	s_setprio 0
	s_barrier
	s_branch .Lpeel2_join

; #define PG8_STAGE(bufoff, gbase, voff) do { _Pragma("unroll") for (int _i = 0; _i < 2; ++_i) \
;         __builtin_amdgcn_global_load_lds((const unsigned*)((const char*)(gbase) + (voff)[_i]), (LAS unsigned*)(lds + (bufoff) + ldsw + _i * 8192), 16, 0, 0); } while (0)
; #define PG8_LDA(dst, b, h) do { _Pragma("unroll") for (int m = 0; m < 4; ++m) _Pragma("unroll") for (int k = 0; k < 2; ++k) dst[m][k] = *(const LAS bf16x8*)(lds + PG8_SA(b, h) + aoff + m * 2048 + k * 1024); } while (0)
; #define PG8_LDB(dst, b, h) do { _Pragma("unroll") for (int n = 0; n < 2; ++n) _Pragma("unroll") for (int k = 0; k < 2; ++k) dst[n][k] = *(const LAS bf16x8*)(lds + PG8_SB(b, h) + boff + n * 2048 + k * 1024); } while (0)
; #define PG8_MMA(ai, bj, At, Bt) do { __builtin_amdgcn_s_setprio(1); _Pragma("unroll") for (int m = 0; m < 4; ++m) _Pragma("unroll") for (int n = 0; n < 2; ++n) _Pragma("unroll") for (int k = 0; k < 2; ++k) \
;         acc[ai][bj][m][n] = __builtin_amdgcn_mfma_f32_16x16x32_bf16(Bt[n][k], At[m][k], acc[ai][bj][m][n], 0, 0, 0); __builtin_amdgcn_s_setprio(0); } while (0)
; #define PG8_WAIT_V(n) asm volatile("s_waitcnt vmcnt(" #n ")" ::: "memory")
; #define PG8_WAIT_L(n) asm volatile("s_waitcnt lgkmcnt(" #n ")" ::: "memory")
; #define PG8_BAR __builtin_amdgcn_s_barrier()
; #define PG8_SCHED __builtin_amdgcn_sched_barrier(0)
; template <class Epi, class Sched>
; __device__ __forceinline__ void gemm_phase(LAS unsigned char* lds, const int lda, const int ldb, const int K, const Sched& S, const Epi& E) {
;     ...
;             PG8_LDB(B0, 1, 0); PG8_LDB(B1, 1, 1); PG8_SCHED; PG8_LDA(At, 1, 0); PG8_STAGE(PG8_SA(0, 1), a2 + hstepA, voffA);
;             PG8_WAIT_V(8); PG8_WAIT_L(0); PG8_BAR; PG8_MMA(0, 0, At, B0); PG8_MMA(0, 1, At, B1); PG8_BAR; PG8_SCHED;
;             PG8_LDA(At, 1, 1); PG8_STAGE(PG8_SB(1, 0), b3, voffB); PG8_STAGE(PG8_SB(1, 1), b3 + hstepB, voffB); PG8_STAGE(PG8_SA(1, 0), a3, voffA);
;             PG8_WAIT_V(8); PG8_WAIT_L(0); PG8_BAR;
;             if (last) E.pre(cur, wr, fr, rsv);
;             PG8_MMA(1, 0, At, B0); PG8_MMA(1, 1, At, B1); PG8_BAR; PG8_SCHED;
;         }
;         if (wr == 0) PG8_BAR;
.Lpeel2_join:
	s_add_i32 s51, 0, 0x18000
	s_add_i32 s62, 0, 0x1c000
	v_add_u32_e32 v142, s51, v186
	v_add_u32_e32 v174, s62, v186
	ds_read_b128 v[130:133], v142
	ds_read_b128 v[134:137], v142 offset:1024
	ds_read_b128 v[138:141], v142 offset:2048
	ds_read_b128 v[142:145], v142 offset:3072
	ds_read_b128 v[146:149], v174
	ds_read_b128 v[150:153], v174 offset:1024
	ds_read_b128 v[170:173], v174 offset:2048
	ds_read_b128 v[174:177], v174 offset:3072
	s_add_u32 s22, s22, 0xb0000
	s_addc_u32 s23, s23, 0
	s_mov_b32 m0, s28
	ds_read_b128 v[178:181], v190 offset:32768
	ds_read_b128 v[182:185], v190 offset:33792
	ds_read_b128 v[196:199], v190 offset:34816
	ds_read_b128 v[200:203], v190 offset:35840
	ds_read_b128 v[204:207], v190 offset:36864
	ds_read_b128 v[208:211], v190 offset:37888
	ds_read_b128 v[212:215], v190 offset:38912
	ds_read_b128 v[216:219], v190 offset:39936
	global_load_lds_dwordx4 v154, s[22:23]
	s_mov_b32 m0, s29
	s_nop 0
	global_load_lds_dwordx4 v158, s[22:23]
	s_waitcnt vmcnt(8)
	s_waitcnt lgkmcnt(0)
	s_barrier
	s_setprio 1
	s_waitcnt lgkmcnt(0)
	v_mfma_f32_16x16x32_bf16 v[126:129], v[130:133], v[178:181], v[126:129]
	v_mfma_f32_16x16x32_bf16 v[122:125], v[138:141], v[178:181], v[122:125]
	v_mfma_f32_16x16x32_bf16 v[110:113], v[130:133], v[196:199], v[110:113]
	v_mfma_f32_16x16x32_bf16 v[106:109], v[138:141], v[196:199], v[106:109]
	v_mfma_f32_16x16x32_bf16 v[94:97], v[130:133], v[204:207], v[94:97]
	v_mfma_f32_16x16x32_bf16 v[90:93], v[138:141], v[204:207], v[90:93]
	v_mfma_f32_16x16x32_bf16 v[78:81], v[130:133], v[212:215], v[78:81]
	v_mfma_f32_16x16x32_bf16 v[74:77], v[138:141], v[212:215], v[74:77]
	v_mfma_f32_16x16x32_bf16 v[126:129], v[134:137], v[182:185], v[126:129]
	v_mfma_f32_16x16x32_bf16 v[122:125], v[142:145], v[182:185], v[122:125]
	v_mfma_f32_16x16x32_bf16 v[110:113], v[134:137], v[200:203], v[110:113]
	v_mfma_f32_16x16x32_bf16 v[106:109], v[142:145], v[200:203], v[106:109]
	v_mfma_f32_16x16x32_bf16 v[94:97], v[134:137], v[208:211], v[94:97]
	v_mfma_f32_16x16x32_bf16 v[90:93], v[142:145], v[208:211], v[90:93]
	v_mfma_f32_16x16x32_bf16 v[78:81], v[134:137], v[216:219], v[78:81]
	v_mfma_f32_16x16x32_bf16 v[74:77], v[142:145], v[216:219], v[74:77]
	s_setprio 0
	s_setprio 1
	v_mfma_f32_16x16x32_bf16 v[118:121], v[146:149], v[178:181], v[118:121]
	v_mfma_f32_16x16x32_bf16 v[114:117], v[170:173], v[178:181], v[114:117]
	v_mfma_f32_16x16x32_bf16 v[102:105], v[146:149], v[196:199], v[102:105]
	v_mfma_f32_16x16x32_bf16 v[98:101], v[170:173], v[196:199], v[98:101]
	v_mfma_f32_16x16x32_bf16 v[86:89], v[146:149], v[204:207], v[86:89]
	v_mfma_f32_16x16x32_bf16 v[82:85], v[170:173], v[204:207], v[82:85]
	v_mfma_f32_16x16x32_bf16 v[70:73], v[146:149], v[212:215], v[70:73]
	v_mfma_f32_16x16x32_bf16 v[66:69], v[170:173], v[212:215], v[66:69]
	v_mfma_f32_16x16x32_bf16 v[118:121], v[150:153], v[182:185], v[118:121]
	v_mfma_f32_16x16x32_bf16 v[114:117], v[174:177], v[182:185], v[114:117]
	v_mfma_f32_16x16x32_bf16 v[102:105], v[150:153], v[200:203], v[102:105]
	v_mfma_f32_16x16x32_bf16 v[98:101], v[174:177], v[200:203], v[98:101]
	v_mfma_f32_16x16x32_bf16 v[86:89], v[150:153], v[208:211], v[86:89]
	v_mfma_f32_16x16x32_bf16 v[82:85], v[174:177], v[208:211], v[82:85]
	v_mfma_f32_16x16x32_bf16 v[70:73], v[150:153], v[216:219], v[70:73]
	v_mfma_f32_16x16x32_bf16 v[66:69], v[174:177], v[216:219], v[66:69]
	s_setprio 0
	s_barrier
	s_add_i32 s22, s51, s25
	s_mov_b32 m0, s22
	ds_read_b128 v[178:181], v190 offset:49152
	ds_read_b128 v[182:185], v190 offset:50176
	ds_read_b128 v[196:199], v190 offset:51200
	ds_read_b128 v[200:203], v190 offset:52224
	ds_read_b128 v[204:207], v190 offset:53248
	ds_read_b128 v[208:211], v190 offset:54272
	ds_read_b128 v[212:215], v190 offset:55296
	ds_read_b128 v[216:219], v190 offset:56320
	global_load_lds_dwordx4 v192, s[20:21]
	s_add_i32 m0, s22, 0x2000
	s_add_u32 s20, s20, 0xb0080
	s_addc_u32 s21, s21, 0
	s_add_i32 s22, s62, s25
	global_load_lds_dwordx4 v193, s[98:99]
	s_mov_b32 m0, s22
	s_nop 0
	global_load_lds_dwordx4 v156, s[20:21]
	s_add_i32 m0, s22, 0x2000
	s_nop 0
	global_load_lds_dwordx4 v160, s[20:21]
	s_mov_b32 m0, s33
	s_nop 0
	global_load_lds_dwordx4 v220, s[100:101]
	s_mov_b32 m0, s36
	s_nop 0
	global_load_lds_dwordx4 v221, s[100:101]
	s_waitcnt vmcnt(8)
	s_waitcnt lgkmcnt(0)
	s_barrier
	s_setprio 1
	s_waitcnt lgkmcnt(0)
	v_mfma_f32_16x16x32_bf16 v[62:65], v[130:133], v[178:181], v[62:65]
	v_mfma_f32_16x16x32_bf16 v[58:61], v[138:141], v[178:181], v[58:61]
	v_mfma_f32_16x16x32_bf16 v[46:49], v[130:133], v[196:199], v[46:49]
	v_mfma_f32_16x16x32_bf16 v[42:45], v[138:141], v[196:199], v[42:45]
	v_mfma_f32_16x16x32_bf16 v[30:33], v[130:133], v[204:207], v[30:33]
	v_mfma_f32_16x16x32_bf16 v[26:29], v[138:141], v[204:207], v[26:29]
	v_mfma_f32_16x16x32_bf16 v[14:17], v[130:133], v[212:215], v[14:17]
	v_mfma_f32_16x16x32_bf16 v[10:13], v[138:141], v[212:215], v[10:13]
	v_mfma_f32_16x16x32_bf16 v[62:65], v[134:137], v[182:185], v[62:65]
	v_mfma_f32_16x16x32_bf16 v[58:61], v[142:145], v[182:185], v[58:61]
	v_mfma_f32_16x16x32_bf16 v[46:49], v[134:137], v[200:203], v[46:49]
	v_mfma_f32_16x16x32_bf16 v[42:45], v[142:145], v[200:203], v[42:45]
	v_mfma_f32_16x16x32_bf16 v[30:33], v[134:137], v[208:211], v[30:33]
	v_mfma_f32_16x16x32_bf16 v[26:29], v[142:145], v[208:211], v[26:29]
	v_mfma_f32_16x16x32_bf16 v[14:17], v[134:137], v[216:219], v[14:17]
	v_mfma_f32_16x16x32_bf16 v[10:13], v[142:145], v[216:219], v[10:13]
	s_setprio 0
	s_setprio 1
	v_mfma_f32_16x16x32_bf16 v[54:57], v[146:149], v[178:181], v[54:57]
	v_mfma_f32_16x16x32_bf16 v[50:53], v[170:173], v[178:181], v[50:53]
	v_mfma_f32_16x16x32_bf16 v[38:41], v[146:149], v[196:199], v[38:41]
	v_mfma_f32_16x16x32_bf16 v[34:37], v[170:173], v[196:199], v[34:37]
	v_mfma_f32_16x16x32_bf16 v[22:25], v[146:149], v[204:207], v[22:25]
	v_mfma_f32_16x16x32_bf16 v[18:21], v[170:173], v[204:207], v[18:21]
	v_mfma_f32_16x16x32_bf16 v[6:9], v[146:149], v[212:215], v[6:9]
	v_mfma_f32_16x16x32_bf16 v[2:5], v[170:173], v[212:215], v[2:5]
	v_mfma_f32_16x16x32_bf16 v[54:57], v[150:153], v[182:185], v[54:57]
	v_mfma_f32_16x16x32_bf16 v[50:53], v[174:177], v[182:185], v[50:53]
	v_mfma_f32_16x16x32_bf16 v[38:41], v[150:153], v[200:203], v[38:41]
	v_mfma_f32_16x16x32_bf16 v[34:37], v[174:177], v[200:203], v[34:37]
	v_mfma_f32_16x16x32_bf16 v[22:25], v[150:153], v[208:211], v[22:25]
	v_mfma_f32_16x16x32_bf16 v[18:21], v[174:177], v[208:211], v[18:21]
	v_mfma_f32_16x16x32_bf16 v[6:9], v[150:153], v[216:219], v[6:9]
	v_mfma_f32_16x16x32_bf16 v[2:5], v[174:177], v[216:219], v[2:5]
	s_setprio 0
	s_barrier
	s_add_i32 s50, s50, 2
	s_add_u32 s18, s18, 0x100
	s_addc_u32 s19, s19, 0
	s_add_u32 s48, s48, 0x100
	s_addc_u32 s49, s49, 0
	s_cmp_gt_u32 s50, 41
	s_cbranch_scc0 .LBB0_326
	s_and_b64 vcc, exec, s[12:13]
	s_cbranch_vccz .LBB0_329
	s_barrier

; #define PG8_STAGE(bufoff, gbase, voff) do { _Pragma("unroll") for (int _i = 0; _i < 2; ++_i) \
;         __builtin_amdgcn_global_load_lds((const unsigned*)((const char*)(gbase) + (voff)[_i]), (LAS unsigned*)(lds + (bufoff) + ldsw + _i * 8192), 16, 0, 0); } while (0)
; #define PG8_LDA(dst, b, h) do { _Pragma("unroll") for (int m = 0; m < 4; ++m) _Pragma("unroll") for (int k = 0; k < 2; ++k) dst[m][k] = *(const LAS bf16x8*)(lds + PG8_SA(b, h) + aoff + m * 2048 + k * 1024); } while (0)
; template <class Epi, class Sched>
; __device__ __forceinline__ void gemm_phase(LAS unsigned char* lds, const int lda, const int ldb, const int K, const Sched& S, const Epi& E) {
;     ...
;     Unit cur, nxt; int ui = 0;
;     if (!S.next(0, cur)) return;
;     f32x4 acc[2][2][4][2];
; #pragma unroll
;     for (int a = 0; a < 2; ++a)
; #pragma unroll
;         for (int b = 0; b < 2; ++b)
; #pragma unroll
;             for (int m = 0; m < 4; ++m)
; #pragma unroll
;                 for (int n = 0; n < 2; ++n) acc[a][b][m][n] = (f32x4){0.f, 0.f, 0.f, 0.f};
;     bf16x8 At[4][2], B0[2][2], B1[2][2];
;     float rsv[8];
; #pragma unroll
;     for (int i = 0; i < 8; ++i) rsv[i] = 0.f;
;     const char* cA = cur.A; const char* cB = cur.B;
;     PG8_STAGE(PG8_SB(0, 0), cB, voffB); PG8_STAGE(PG8_SB(0, 1), cB + hstepB, voffB); PG8_STAGE(PG8_SA(0, 0), cA, voffA); PG8_STAGE(PG8_SA(0, 1), cA + hstepA, voffA);
;     if (wr == 1) PG8_BAR;
;     PG8_WAIT_V(2); PG8_BAR;
;     PG8_STAGE(PG8_SB(1, 0), cB + kstep, voffB); PG8_STAGE(PG8_SA(1, 0), cA + kstep, voffA); PG8_STAGE(PG8_SB(1, 1), cB + hstepB + kstep, voffB);
;     PG8_WAIT_V(6); PG8_BAR;
;     for (;;) {
;         const bool has_next = S.next(ui + 1, nxt);
;         const char* nA = has_next ? nxt.A : cA; const char* nB = has_next ? nxt.B : cB;
;         for (int t = 0; t < nt; t += 2) {
;             const bool last = (t == nt - 2);
;             const char* a1 = cA + (size_t)(t + 1) * kstep;
;             const char* a2 = last ? nA : cA + (size_t)(t + 2) * kstep; const char* b2 = last ? nB : cB + (size_t)(t + 2) * kstep;
;             const char* a3 = a2 + kstep; const char* b3 = b2 + kstep;
;             PG8_LDB(B0, 0, 0); PG8_LDB(B1, 0, 1); PG8_SCHED; PG8_LDA(At, 0, 0); PG8_STAGE(PG8_SA(1, 1), a1 + hstepA, voffA);
;             PG8_WAIT_V(8); PG8_WAIT_L(0); PG8_BAR; PG8_MMA(0, 0, At, B0); PG8_MMA(0, 1, At, B1); PG8_BAR; PG8_SCHED;
.LBB0_424:
	s_lshl_b32 s4, s4, 8
	s_ashr_i32 s5, s4, 31
	s_add_u32 s6, s6, 0x40080
	s_addc_u32 s7, s7, 0
	v_lshl_add_u64 v[220:221], s[4:5], 2, v[206:207]
	s_add_u32 s5, s8, 0x100
	s_addc_u32 s51, s9, 0
	s_mov_b32 s69, -2
	v_add_u32_e32 v234, 0x80, v202
	v_add_u32_e32 v235, 0x80, v198
	v_add_u32_e32 v236, 0x80, v204
	v_add_u32_e32 v237, 0x80, v200
	s_add_u32 s8, s6, 0xfffc0080
	s_addc_u32 s9, s7, -1
	s_cmp_eq_u32 s69, 12
	s_cselect_b32 s13, s71, s9
	s_cselect_b32 s12, s70, s8
	s_cselect_b32 s15, s73, s51
	s_cselect_b32 s14, s72, s5
	s_add_i32 s81, s63, s36
	ds_read_b128 v[130:133], v222
	ds_read_b128 v[134:137], v222 offset:1024
	ds_read_b128 v[138:141], v222 offset:2048
	ds_read_b128 v[142:145], v222 offset:3072
	ds_read_b128 v[146:149], v223
	ds_read_b128 v[150:153], v223 offset:1024
	ds_read_b128 v[154:157], v223 offset:2048
	ds_read_b128 v[158:161], v223 offset:3072
	s_add_i32 m0, s39, 0xc000
	s_add_i32 s80, s39, 0xe000
	s_add_i32 s82, s81, 0x2000
	s_add_u32 s16, s14, 0x40000
	s_addc_u32 s17, s15, 0
	s_add_i32 s83, s64, s36
	s_add_i32 s84, s83, 0x2000
	s_add_i32 s85, 0, 0x18000
	s_add_i32 s86, 0, 0x1c000
	s_add_u32 s10, s12, 0x40000
	s_addc_u32 s11, s13, 0
	s_add_i32 s75, s85, s36
	s_add_i32 s74, s75, 0x2000
	s_add_u32 s8, s14, 0x40080
	s_addc_u32 s9, s15, 0
	s_add_i32 s79, s86, s36
	s_add_i32 s78, s79, 0x2000
	s_cmp_lg_u32 s69, 12
	ds_read_b128 v[162:165], v224
	ds_read_b128 v[166:169], v224 offset:1024
	ds_read_b128 v[170:173], v224 offset:2048
	ds_read_b128 v[174:177], v224 offset:3072
	ds_read_b128 v[178:181], v224 offset:4096
	ds_read_b128 v[182:185], v224 offset:5120
	ds_read_b128 v[186:189], v224 offset:6144
	ds_read_b128 v[190:193], v224 offset:7168
	global_load_lds_dwordx4 v212, s[6:7]
	s_mov_b32 m0, s80
	s_nop 0
	global_load_lds_dwordx4 v214, s[6:7]
	s_waitcnt vmcnt(8)
	s_waitcnt lgkmcnt(0)
	s_barrier
	s_setprio 1
	s_waitcnt lgkmcnt(0)
	v_mfma_f32_16x16x32_bf16 v[126:129], v[130:133], v[162:165], 0
	v_mfma_f32_16x16x32_bf16 v[118:121], v[138:141], v[162:165], 0
	v_mfma_f32_16x16x32_bf16 v[110:113], v[130:133], v[170:173], 0
	v_mfma_f32_16x16x32_bf16 v[102:105], v[138:141], v[170:173], 0
	v_mfma_f32_16x16x32_bf16 v[94:97], v[130:133], v[178:181], 0
	v_mfma_f32_16x16x32_bf16 v[86:89], v[138:141], v[178:181], 0
	v_mfma_f32_16x16x32_bf16 v[78:81], v[130:133], v[186:189], 0
	v_mfma_f32_16x16x32_bf16 v[70:73], v[138:141], v[186:189], 0
	v_mfma_f32_16x16x32_bf16 v[126:129], v[134:137], v[166:169], v[126:129]
	v_mfma_f32_16x16x32_bf16 v[118:121], v[142:145], v[166:169], v[118:121]
	v_mfma_f32_16x16x32_bf16 v[110:113], v[134:137], v[174:177], v[110:113]
	v_mfma_f32_16x16x32_bf16 v[102:105], v[142:145], v[174:177], v[102:105]
	v_mfma_f32_16x16x32_bf16 v[94:97], v[134:137], v[182:185], v[94:97]
	v_mfma_f32_16x16x32_bf16 v[86:89], v[142:145], v[182:185], v[86:89]
	v_mfma_f32_16x16x32_bf16 v[78:81], v[134:137], v[190:193], v[78:81]
	v_mfma_f32_16x16x32_bf16 v[70:73], v[142:145], v[190:193], v[70:73]
	s_setprio 0
	s_setprio 1
	v_mfma_f32_16x16x32_bf16 v[122:125], v[146:149], v[162:165], 0
	v_mfma_f32_16x16x32_bf16 v[114:117], v[154:157], v[162:165], 0
	v_mfma_f32_16x16x32_bf16 v[106:109], v[146:149], v[170:173], 0
	v_mfma_f32_16x16x32_bf16 v[98:101], v[154:157], v[170:173], 0
	v_mfma_f32_16x16x32_bf16 v[90:93], v[146:149], v[178:181], 0
	v_mfma_f32_16x16x32_bf16 v[82:85], v[154:157], v[178:181], 0
	v_mfma_f32_16x16x32_bf16 v[74:77], v[146:149], v[186:189], 0
	v_mfma_f32_16x16x32_bf16 v[66:69], v[154:157], v[186:189], 0
	v_mfma_f32_16x16x32_bf16 v[122:125], v[150:153], v[166:169], v[122:125]
	v_mfma_f32_16x16x32_bf16 v[114:117], v[158:161], v[166:169], v[114:117]
	v_mfma_f32_16x16x32_bf16 v[106:109], v[150:153], v[174:177], v[106:109]
	v_mfma_f32_16x16x32_bf16 v[98:101], v[158:161], v[174:177], v[98:101]
	v_mfma_f32_16x16x32_bf16 v[90:93], v[150:153], v[182:185], v[90:93]
	v_mfma_f32_16x16x32_bf16 v[82:85], v[158:161], v[182:185], v[82:85]
	v_mfma_f32_16x16x32_bf16 v[74:77], v[150:153], v[190:193], v[74:77]
	v_mfma_f32_16x16x32_bf16 v[66:69], v[158:161], v[190:193], v[66:69]
	s_setprio 0
	s_barrier
; #define PG8_STAGE(bufoff, gbase, voff) do { _Pragma("unroll") for (int _i = 0; _i < 2; ++_i) \
;         __builtin_amdgcn_global_load_lds((const unsigned*)((const char*)(gbase) + (voff)[_i]), (LAS unsigned*)(lds + (bufoff) + ldsw + _i * 8192), 16, 0, 0); } while (0)
; #define PG8_LDA(dst, b, h) do { _Pragma("unroll") for (int m = 0; m < 4; ++m) _Pragma("unroll") for (int k = 0; k < 2; ++k) dst[m][k] = *(const LAS bf16x8*)(lds + PG8_SA(b, h) + aoff + m * 2048 + k * 1024); } while (0)
; #define PG8_MMA(ai, bj, At, Bt) do { __builtin_amdgcn_s_setprio(1); _Pragma("unroll") for (int m = 0; m < 4; ++m) _Pragma("unroll") for (int n = 0; n < 2; ++n) _Pragma("unroll") for (int k = 0; k < 2; ++k) \
;         acc[ai][bj][m][n] = __builtin_amdgcn_mfma_f32_16x16x32_bf16(Bt[n][k], At[m][k], acc[ai][bj][m][n], 0, 0, 0); __builtin_amdgcn_s_setprio(0); } while (0)
; #define PG8_WAIT_V(n) asm volatile("s_waitcnt vmcnt(" #n ")" ::: "memory")
; #define PG8_WAIT_L(n) asm volatile("s_waitcnt lgkmcnt(" #n ")" ::: "memory")
; #define PG8_BAR __builtin_amdgcn_s_barrier()
; #define PG8_SCHED __builtin_amdgcn_sched_barrier(0)
; template <class Epi, class Sched>
; __device__ __forceinline__ void gemm_phase(LAS unsigned char* lds, const int lda, const int ldb, const int K, const Sched& S, const Epi& E) {
;     ...
;             PG8_LDA(At, 0, 1); PG8_STAGE(PG8_SB(0, 0), b2, voffB); PG8_STAGE(PG8_SB(0, 1), b2 + hstepB, voffB); PG8_STAGE(PG8_SA(0, 0), a2, voffA);
;             PG8_WAIT_V(8); PG8_WAIT_L(0); PG8_BAR; PG8_MMA(1, 0, At, B0); PG8_MMA(1, 1, At, B1); PG8_BAR; PG8_SCHED;
	s_mov_b32 m0, s81
	ds_read_b128 v[162:165], v224 offset:16384
	ds_read_b128 v[166:169], v224 offset:17408
	ds_read_b128 v[170:173], v224 offset:18432
	ds_read_b128 v[174:177], v224 offset:19456
	ds_read_b128 v[178:181], v224 offset:20480
	ds_read_b128 v[182:185], v224 offset:21504
	ds_read_b128 v[186:189], v224 offset:22528
	ds_read_b128 v[190:193], v224 offset:23552
	global_load_lds_dwordx4 v202, s[14:15]
	s_mov_b32 m0, s82
	s_nop 0
	global_load_lds_dwordx4 v198, s[14:15]
	s_mov_b32 m0, s83
	s_nop 0
	global_load_lds_dwordx4 v202, s[16:17]
	s_mov_b32 m0, s84
	s_nop 0
	global_load_lds_dwordx4 v198, s[16:17]
	s_mov_b32 m0, s39
	s_nop 0
	global_load_lds_dwordx4 v204, s[12:13]
	s_mov_b32 m0, s40
	s_nop 0
	global_load_lds_dwordx4 v200, s[12:13]
	s_waitcnt vmcnt(8)
	s_waitcnt lgkmcnt(0)
	s_barrier
	s_setprio 1
	s_waitcnt lgkmcnt(0)
	v_mfma_f32_16x16x32_bf16 v[62:65], v[130:133], v[162:165], 0
	v_mfma_f32_16x16x32_bf16 v[54:57], v[138:141], v[162:165], 0
	v_mfma_f32_16x16x32_bf16 v[46:49], v[130:133], v[170:173], 0
	v_mfma_f32_16x16x32_bf16 v[38:41], v[138:141], v[170:173], 0
	v_mfma_f32_16x16x32_bf16 v[30:33], v[130:133], v[178:181], 0
	v_mfma_f32_16x16x32_bf16 v[22:25], v[138:141], v[178:181], 0
	v_mfma_f32_16x16x32_bf16 v[14:17], v[130:133], v[186:189], 0
	v_mfma_f32_16x16x32_bf16 v[6:9], v[138:141], v[186:189], 0
	v_mfma_f32_16x16x32_bf16 v[62:65], v[134:137], v[166:169], v[62:65]
	v_mfma_f32_16x16x32_bf16 v[54:57], v[142:145], v[166:169], v[54:57]
	v_mfma_f32_16x16x32_bf16 v[46:49], v[134:137], v[174:177], v[46:49]
	v_mfma_f32_16x16x32_bf16 v[38:41], v[142:145], v[174:177], v[38:41]
	v_mfma_f32_16x16x32_bf16 v[30:33], v[134:137], v[182:185], v[30:33]
	v_mfma_f32_16x16x32_bf16 v[22:25], v[142:145], v[182:185], v[22:25]
	v_mfma_f32_16x16x32_bf16 v[14:17], v[134:137], v[190:193], v[14:17]
	v_mfma_f32_16x16x32_bf16 v[6:9], v[142:145], v[190:193], v[6:9]
	s_setprio 0
	s_setprio 1
	v_mfma_f32_16x16x32_bf16 v[58:61], v[146:149], v[162:165], 0
	v_mfma_f32_16x16x32_bf16 v[50:53], v[154:157], v[162:165], 0
	v_mfma_f32_16x16x32_bf16 v[42:45], v[146:149], v[170:173], 0
	v_mfma_f32_16x16x32_bf16 v[34:37], v[154:157], v[170:173], 0
	v_mfma_f32_16x16x32_bf16 v[26:29], v[146:149], v[178:181], 0
	v_mfma_f32_16x16x32_bf16 v[18:21], v[154:157], v[178:181], 0
	v_mfma_f32_16x16x32_bf16 v[10:13], v[146:149], v[186:189], 0
	v_mfma_f32_16x16x32_bf16 v[2:5], v[154:157], v[186:189], 0
	v_mfma_f32_16x16x32_bf16 v[58:61], v[150:153], v[166:169], v[58:61]
	v_mfma_f32_16x16x32_bf16 v[50:53], v[158:161], v[166:169], v[50:53]
	v_mfma_f32_16x16x32_bf16 v[42:45], v[150:153], v[174:177], v[42:45]
	v_mfma_f32_16x16x32_bf16 v[34:37], v[158:161], v[174:177], v[34:37]
	v_mfma_f32_16x16x32_bf16 v[26:29], v[150:153], v[182:185], v[26:29]
	v_mfma_f32_16x16x32_bf16 v[18:21], v[158:161], v[182:185], v[18:21]
	v_mfma_f32_16x16x32_bf16 v[10:13], v[150:153], v[190:193], v[10:13]
	v_mfma_f32_16x16x32_bf16 v[2:5], v[158:161], v[190:193], v[2:5]
	s_setprio 0
	s_barrier
	s_branch .Lpeel3_join

; #define PG8_STAGE(bufoff, gbase, voff) do { _Pragma("unroll") for (int _i = 0; _i < 2; ++_i) \
;         __builtin_amdgcn_global_load_lds((const unsigned*)((const char*)(gbase) + (voff)[_i]), (LAS unsigned*)(lds + (bufoff) + ldsw + _i * 8192), 16, 0, 0); } while (0)
; #define PG8_LDA(dst, b, h) do { _Pragma("unroll") for (int m = 0; m < 4; ++m) _Pragma("unroll") for (int k = 0; k < 2; ++k) dst[m][k] = *(const LAS bf16x8*)(lds + PG8_SA(b, h) + aoff + m * 2048 + k * 1024); } while (0)
; #define PG8_LDB(dst, b, h) do { _Pragma("unroll") for (int n = 0; n < 2; ++n) _Pragma("unroll") for (int k = 0; k < 2; ++k) dst[n][k] = *(const LAS bf16x8*)(lds + PG8_SB(b, h) + boff + n * 2048 + k * 1024); } while (0)
; #define PG8_MMA(ai, bj, At, Bt) do { __builtin_amdgcn_s_setprio(1); _Pragma("unroll") for (int m = 0; m < 4; ++m) _Pragma("unroll") for (int n = 0; n < 2; ++n) _Pragma("unroll") for (int k = 0; k < 2; ++k) \
;         acc[ai][bj][m][n] = __builtin_amdgcn_mfma_f32_16x16x32_bf16(Bt[n][k], At[m][k], acc[ai][bj][m][n], 0, 0, 0); __builtin_amdgcn_s_setprio(0); } while (0)
; #define PG8_WAIT_V(n) asm volatile("s_waitcnt vmcnt(" #n ")" ::: "memory")
; #define PG8_WAIT_L(n) asm volatile("s_waitcnt lgkmcnt(" #n ")" ::: "memory")
; #define PG8_BAR __builtin_amdgcn_s_barrier()
; #define PG8_SCHED __builtin_amdgcn_sched_barrier(0)
; template <class Epi, class Sched>
; __device__ __forceinline__ void gemm_phase(LAS unsigned char* lds, const int lda, const int ldb, const int K, const Sched& S, const Epi& E) {
;     ...
;             PG8_LDB(B0, 1, 0); PG8_LDB(B1, 1, 1); PG8_SCHED; PG8_LDA(At, 1, 0); PG8_STAGE(PG8_SA(0, 1), a2 + hstepA, voffA);
;             PG8_WAIT_V(8); PG8_WAIT_L(0); PG8_BAR; PG8_MMA(0, 0, At, B0); PG8_MMA(0, 1, At, B1); PG8_BAR; PG8_SCHED;
;             PG8_LDA(At, 1, 1); PG8_STAGE(PG8_SB(1, 0), b3, voffB); PG8_STAGE(PG8_SB(1, 1), b3 + hstepB, voffB); PG8_STAGE(PG8_SA(1, 0), a3, voffA);
;             PG8_WAIT_V(8); PG8_WAIT_L(0); PG8_BAR;
;             if (last) E.pre(cur, wr, fr, rsv);
;     __device__ __forceinline__ void pre(const pg8::Unit& u, int wr, int fr, float (&rsv)[8]) const {
;         const float* p = ss + u.pm * 256 + wr * 64 + fr;
; #pragma unroll
;         for (int ai = 0; ai < 2; ++ai)
; #pragma unroll
;             for (int m = 0; m < 4; ++m) rsv[ai * 4 + m] = p[ai * 128 + m * 16];
;     }
.Lpeel3_join:
	v_add_u32_e32 v130, s85, v195
	v_add_u32_e32 v142, s86, v195
	ds_read_b128 v[146:149], v130
	ds_read_b128 v[150:153], v130 offset:1024
	ds_read_b128 v[154:157], v130 offset:2048
	ds_read_b128 v[158:161], v130 offset:3072
	ds_read_b128 v[130:133], v142
	ds_read_b128 v[134:137], v142 offset:1024
	ds_read_b128 v[138:141], v142 offset:2048
	ds_read_b128 v[142:145], v142 offset:3072
	s_mov_b32 m0, s41
	ds_read_b128 v[162:165], v224 offset:32768
	ds_read_b128 v[166:169], v224 offset:33792
	ds_read_b128 v[170:173], v224 offset:34816
	ds_read_b128 v[174:177], v224 offset:35840
	ds_read_b128 v[178:181], v224 offset:36864
	ds_read_b128 v[182:185], v224 offset:37888
	ds_read_b128 v[186:189], v224 offset:38912
	ds_read_b128 v[190:193], v224 offset:39936
	global_load_lds_dwordx4 v204, s[10:11]
	s_mov_b32 m0, s42
	s_nop 0
	global_load_lds_dwordx4 v200, s[10:11]
	s_waitcnt vmcnt(8)
	s_waitcnt lgkmcnt(0)
	s_barrier
	s_setprio 1
	s_waitcnt lgkmcnt(0)
	v_mfma_f32_16x16x32_bf16 v[126:129], v[146:149], v[162:165], v[126:129]
	v_mfma_f32_16x16x32_bf16 v[118:121], v[154:157], v[162:165], v[118:121]
	v_mfma_f32_16x16x32_bf16 v[110:113], v[146:149], v[170:173], v[110:113]
	v_mfma_f32_16x16x32_bf16 v[102:105], v[154:157], v[170:173], v[102:105]
	v_mfma_f32_16x16x32_bf16 v[94:97], v[146:149], v[178:181], v[94:97]
	v_mfma_f32_16x16x32_bf16 v[86:89], v[154:157], v[178:181], v[86:89]
	v_mfma_f32_16x16x32_bf16 v[78:81], v[146:149], v[186:189], v[78:81]
	v_mfma_f32_16x16x32_bf16 v[70:73], v[154:157], v[186:189], v[70:73]
	v_mfma_f32_16x16x32_bf16 v[126:129], v[150:153], v[166:169], v[126:129]
	v_mfma_f32_16x16x32_bf16 v[118:121], v[158:161], v[166:169], v[118:121]
	v_mfma_f32_16x16x32_bf16 v[110:113], v[150:153], v[174:177], v[110:113]
	v_mfma_f32_16x16x32_bf16 v[102:105], v[158:161], v[174:177], v[102:105]
	v_mfma_f32_16x16x32_bf16 v[94:97], v[150:153], v[182:185], v[94:97]
	v_mfma_f32_16x16x32_bf16 v[86:89], v[158:161], v[182:185], v[86:89]
	v_mfma_f32_16x16x32_bf16 v[78:81], v[150:153], v[190:193], v[78:81]
	v_mfma_f32_16x16x32_bf16 v[70:73], v[158:161], v[190:193], v[70:73]
	s_setprio 0
	s_setprio 1
	v_mfma_f32_16x16x32_bf16 v[122:125], v[130:133], v[162:165], v[122:125]
	v_mfma_f32_16x16x32_bf16 v[114:117], v[138:141], v[162:165], v[114:117]
	v_mfma_f32_16x16x32_bf16 v[106:109], v[130:133], v[170:173], v[106:109]
	v_mfma_f32_16x16x32_bf16 v[98:101], v[138:141], v[170:173], v[98:101]
	v_mfma_f32_16x16x32_bf16 v[90:93], v[130:133], v[178:181], v[90:93]
	v_mfma_f32_16x16x32_bf16 v[82:85], v[138:141], v[178:181], v[82:85]
	v_mfma_f32_16x16x32_bf16 v[74:77], v[130:133], v[186:189], v[74:77]
	v_mfma_f32_16x16x32_bf16 v[66:69], v[138:141], v[186:189], v[66:69]
	v_mfma_f32_16x16x32_bf16 v[122:125], v[134:137], v[166:169], v[122:125]
	v_mfma_f32_16x16x32_bf16 v[114:117], v[142:145], v[166:169], v[114:117]
	v_mfma_f32_16x16x32_bf16 v[106:109], v[134:137], v[174:177], v[106:109]
	v_mfma_f32_16x16x32_bf16 v[98:101], v[142:145], v[174:177], v[98:101]
	v_mfma_f32_16x16x32_bf16 v[90:93], v[134:137], v[182:185], v[90:93]
	v_mfma_f32_16x16x32_bf16 v[82:85], v[142:145], v[182:185], v[82:85]
	v_mfma_f32_16x16x32_bf16 v[74:77], v[134:137], v[190:193], v[74:77]
	v_mfma_f32_16x16x32_bf16 v[66:69], v[142:145], v[190:193], v[66:69]
	s_setprio 0
	s_barrier
	s_mov_b32 m0, s75
	ds_read_b128 v[186:189], v224 offset:49152
	ds_read_b128 v[190:193], v224 offset:50176
	ds_read_b128 v[178:181], v224 offset:51200
	ds_read_b128 v[182:185], v224 offset:52224
	ds_read_b128 v[170:173], v224 offset:53248
	ds_read_b128 v[174:177], v224 offset:54272
	ds_read_b128 v[162:165], v224 offset:55296
	ds_read_b128 v[166:169], v224 offset:56320
	global_load_lds_dwordx4 v234, s[14:15]
	s_mov_b32 m0, s74
	s_nop 0
	global_load_lds_dwordx4 v235, s[14:15]
	s_mov_b32 m0, s79
	s_nop 0
	global_load_lds_dwordx4 v202, s[8:9]
	s_mov_b32 m0, s78
	s_nop 0
	global_load_lds_dwordx4 v198, s[8:9]
	s_mov_b32 m0, s43
	s_nop 0
	global_load_lds_dwordx4 v236, s[12:13]
	s_mov_b32 m0, s44
	s_nop 0
	global_load_lds_dwordx4 v237, s[12:13]
	s_waitcnt vmcnt(8)
	s_waitcnt lgkmcnt(0)
	s_barrier
	s_cbranch_scc1 .LBB0_425
	global_load_dword v233, v[220:221], off
	global_load_dword v232, v[220:221], off offset:64
	global_load_dword v231, v[220:221], off offset:128
	global_load_dword v230, v[220:221], off offset:192
	global_load_dword v229, v[220:221], off offset:512
	global_load_dword v228, v[220:221], off offset:576
	global_load_dword v227, v[220:221], off offset:640
	global_load_dword v226, v[220:221], off offset:704
	s_branch .LBB0_425

; __device__ __forceinline__ f32x4 mfma16(bf16x8 a, bf16x8 b, f32x4 c) { return __builtin_amdgcn_mfma_f32_16x16x32_bf16(a, b, c, 0, 0, 0); }
; __device__ __forceinline__ void gates_phase(const Args& a) {
;     const int tid = threadIdx.x, lane = tid & 63, wave = __builtin_amdgcn_readfirstlane(tid >> 6), g = lane >> 4, c16 = lane & 15;
;     const int gw = blockIdx.x * 8 + wave, NGW = gridDim.x * 8;
;     const bf16_t* XB = (const bf16_t*)(a.ws + WS_XB); const bf16_t* WG = (const bf16_t*)(a.ws + WS_WG);
;     const float* PS1 = (const float*)(a.ws + WS_PS1); float* GATES = (float*)(a.ws + WS_GATES);
;     const float bias = a.in[8][c16]; const bool isf = (c16 >> 2) & 1;
;     for (int it = gw; it < T / 16; it += NGW) {
;         const int r0 = it * 16; f32x4 acc = {0.f, 0.f, 0.f, 0.f};
;         const bf16_t* ap = XB + (size_t)(r0 + c16) * D + 8 * g; const bf16_t* bp = WG + (size_t)c16 * D + 8 * g;
; #pragma unroll 8
;         for (int kk = 0; kk < 32; ++kk) { const bf16x8 av = *(const bf16x8*)(ap + 32 * kk); const bf16x8 bv = *(const bf16x8*)(bp + 32 * kk); acc = mfma16(av, bv, acc); }
.LBB0_438:
	v_readfirstlane_b32 s0, v194
	s_lshr_b32 s4, s0, 6
	s_lshl_b32 s0, s2, 3
	s_add_i32 s3, s4, s0
	s_cmpk_gt_i32 s3, 0x17ff
	s_cbranch_scc1 .LBB0_451
	v_readlane_b32 s68, v253, 1
	s_waitcnt lgkmcnt(0)
	v_lshlrev_b64 v[2:3], 2, v[196:197]
	v_readlane_b32 s69, v253, 2
	v_bfe_u32 v8, v194, 4, 2
	v_lshlrev_b32_e32 v22, 2, v8
	v_lshl_add_u64 v[4:5], s[68:69], 0, v[2:3]
	global_load_dword v1, v[4:5], off
	v_and_b32_e32 v4, 4, v194
	v_cmp_ne_u32_e64 s[0:1], 0, v4
	v_lshlrev_b64 v[4:5], 11, v[196:197]
	v_lshlrev_b32_e32 v8, 4, v8
	s_lshl_b32 s5, s2, 7
	s_lshl_b32 s4, s4, 4
	v_lshl_add_u64 v[2:3], s[54:55], 0, v[2:3]
	s_mov_b64 s[8:9], 0x2f88000
	v_mov_b32_e32 v9, 0
	s_add_i32 s5, s5, s4
	v_or_b32_e32 v4, v4, v8
	s_lshl_b32 s6, s58, 3
	v_lshl_add_u64 v[6:7], v[2:3], 0, s[8:9]
	v_lshl_add_u64 v[10:11], s[54:55], 0, v[8:9]
	v_or_b32_e32 v12, s5, v196
	s_lshl_b32 s7, s58, 7
	v_lshl_add_u64 v[14:15], s[54:55], 0, v[4:5]
	v_mov_b32_e32 v8, 0x358637bd
	s_mov_b32 s8, 0x800000
	s_mov_b32 s9, 0xbfb8aa3b
	s_mov_b32 s10, 0x3f2aaaab
	v_mov_b32_e32 v23, 0x3ecc95a3
	s_mov_b32 s11, 0x3f317218
	s_mov_b32 s12, 0x7f800000
	s_mov_b32 s13, 0x33800000
	v_mov_b32_e32 v16, 0x3f317218
	v_mov_b32_e32 v24, 0x7f800000
	v_mov_b32_e32 v25, 0x7fc00000
	v_mov_b32_e32 v26, 0xff800000
	v_readlane_b32 s70, v253, 3
	v_readlane_b32 s71, v253, 4
	v_readlane_b32 s72, v253, 5
	v_readlane_b32 s73, v253, 6
	v_readlane_b32 s74, v253, 7
	v_readlane_b32 s75, v253, 8
	v_readlane_b32 s76, v253, 9
	v_readlane_b32 s77, v253, 10
	v_readlane_b32 s78, v253, 11
	v_readlane_b32 s79, v253, 12
	v_readlane_b32 s80, v253, 13
	v_readlane_b32 s81, v253, 14
	v_readlane_b32 s82, v253, 15
	v_readlane_b32 s83, v253, 16
	v_add_co_u32_e32 v64, vcc, 0x1a00000, v14
	s_nop 1
	v_addc_co_u32_e32 v65, vcc, 0, v15, vcc
	global_load_dwordx4 v[66:69], v[64:65], off
	global_load_dwordx4 v[70:73], v[64:65], off offset:64
	global_load_dwordx4 v[74:77], v[64:65], off offset:128
	global_load_dwordx4 v[78:81], v[64:65], off offset:192
	global_load_dwordx4 v[82:85], v[64:65], off offset:256
	global_load_dwordx4 v[86:89], v[64:65], off offset:320
	global_load_dwordx4 v[90:93], v[64:65], off offset:384
	global_load_dwordx4 v[94:97], v[64:65], off offset:448
	global_load_dwordx4 v[100:103], v[64:65], off offset:512
	global_load_dwordx4 v[104:107], v[64:65], off offset:576
	global_load_dwordx4 v[108:111], v[64:65], off offset:640
	global_load_dwordx4 v[112:115], v[64:65], off offset:704
	global_load_dwordx4 v[116:119], v[64:65], off offset:768
	global_load_dwordx4 v[120:123], v[64:65], off offset:832
	global_load_dwordx4 v[124:127], v[64:65], off offset:896
	global_load_dwordx4 v[142:145], v[64:65], off offset:960
	global_load_dwordx4 v[146:149], v[64:65], off offset:1024
	global_load_dwordx4 v[150:153], v[64:65], off offset:1088
	global_load_dwordx4 v[154:157], v[64:65], off offset:1152
	global_load_dwordx4 v[158:161], v[64:65], off offset:1216
	global_load_dwordx4 v[162:165], v[64:65], off offset:1280
	global_load_dwordx4 v[166:169], v[64:65], off offset:1344
	global_load_dwordx4 v[170:173], v[64:65], off offset:1408
	global_load_dwordx4 v[184:187], v[64:65], off offset:1472
	global_load_dwordx4 v[188:191], v[64:65], off offset:1536
	global_load_dwordx4 v[198:201], v[64:65], off offset:1600
	global_load_dwordx4 v[202:205], v[64:65], off offset:1664
	global_load_dwordx4 v[206:209], v[64:65], off offset:1728
	global_load_dwordx4 v[210:213], v[64:65], off offset:1792
	global_load_dwordx4 v[218:221], v[64:65], off offset:1856
	global_load_dwordx4 v[222:225], v[64:65], off offset:1920
	global_load_dwordx4 v[226:229], v[64:65], off offset:1984
	s_branch .LBB0_441

; __device__ __forceinline__ f32x4 mfma16(bf16x8 a, bf16x8 b, f32x4 c) { return __builtin_amdgcn_mfma_f32_16x16x32_bf16(a, b, c, 0, 0, 0); }
; __device__ __forceinline__ float row_rs(const float* ss, int row) { return rsqrtf(ss[row] * (1.f / 1024.f) + EPS); }
; __device__ __forceinline__ void gates_phase(const Args& a) {
;     ...
;     for (int it = gw; it < T / 16; it += NGW) {
;         const int r0 = it * 16; f32x4 acc = {0.f, 0.f, 0.f, 0.f};
;         const bf16_t* ap = XB + (size_t)(r0 + c16) * D + 8 * g; const bf16_t* bp = WG + (size_t)c16 * D + 8 * g;
; #pragma unroll 8
;         for (int kk = 0; kk < 32; ++kk) { const bf16x8 av = *(const bf16x8*)(ap + 32 * kk); const bf16x8 bv = *(const bf16x8*)(bp + 32 * kk); acc = mfma16(av, bv, acc); }
; #pragma unroll
;         for (int j = 0; j < 4; ++j) { const int row = r0 + 4 * g + j; float v = acc[j] * row_rs(PS1, row) + bias;
.LBB0_441:
	v_ashrrev_i32_e32 v13, 31, v12
	v_lshlrev_b64 v[2:3], 11, v[12:13]
	v_lshl_add_u64 v[18:19], v[10:11], 0, v[2:3]
	s_mov_b64 s[4:5], 0
	v_mov_b32_e32 v2, 0
	v_mov_b32_e32 v3, v9
	v_mov_b32_e32 v4, v9
	v_mov_b32_e32 v5, v9
	v_add_co_u32_e32 v20, vcc, 0x36a8000, v18
	s_nop 1
	v_addc_co_u32_e32 v21, vcc, 0, v19, vcc
	global_load_dwordx4 v[28:31], v[20:21], off
	global_load_dwordx4 v[32:35], v[20:21], off offset:64
	global_load_dwordx4 v[36:39], v[20:21], off offset:128
	global_load_dwordx4 v[40:43], v[20:21], off offset:192
	global_load_dwordx4 v[44:47], v[20:21], off offset:256
	global_load_dwordx4 v[48:51], v[20:21], off offset:320
	global_load_dwordx4 v[52:55], v[20:21], off offset:384
	global_load_dwordx4 v[56:59], v[20:21], off offset:448
	s_waitcnt vmcnt(7)
	v_mfma_f32_16x16x32_bf16 v[2:5], v[28:31], v[66:69], v[2:5]
	global_load_dwordx4 v[28:31], v[20:21], off offset:512
	s_waitcnt vmcnt(7)
	v_mfma_f32_16x16x32_bf16 v[2:5], v[32:35], v[70:73], v[2:5]
	global_load_dwordx4 v[32:35], v[20:21], off offset:576
	s_waitcnt vmcnt(7)
	v_mfma_f32_16x16x32_bf16 v[2:5], v[36:39], v[74:77], v[2:5]
	global_load_dwordx4 v[36:39], v[20:21], off offset:640
	s_waitcnt vmcnt(7)
	v_mfma_f32_16x16x32_bf16 v[2:5], v[40:43], v[78:81], v[2:5]
	global_load_dwordx4 v[40:43], v[20:21], off offset:704
	s_waitcnt vmcnt(7)
	v_mfma_f32_16x16x32_bf16 v[2:5], v[44:47], v[82:85], v[2:5]
	global_load_dwordx4 v[44:47], v[20:21], off offset:768
	s_waitcnt vmcnt(7)
	v_mfma_f32_16x16x32_bf16 v[2:5], v[48:51], v[86:89], v[2:5]
	global_load_dwordx4 v[48:51], v[20:21], off offset:832
	s_waitcnt vmcnt(7)
	v_mfma_f32_16x16x32_bf16 v[2:5], v[52:55], v[90:93], v[2:5]
	global_load_dwordx4 v[52:55], v[20:21], off offset:896
	s_waitcnt vmcnt(7)
	v_mfma_f32_16x16x32_bf16 v[2:5], v[56:59], v[94:97], v[2:5]
	global_load_dwordx4 v[56:59], v[20:21], off offset:960
	s_waitcnt vmcnt(7)
	v_mfma_f32_16x16x32_bf16 v[2:5], v[28:31], v[100:103], v[2:5]
	global_load_dwordx4 v[28:31], v[20:21], off offset:1024
	s_waitcnt vmcnt(7)
	v_mfma_f32_16x16x32_bf16 v[2:5], v[32:35], v[104:107], v[2:5]
	global_load_dwordx4 v[32:35], v[20:21], off offset:1088
	s_waitcnt vmcnt(7)
	v_mfma_f32_16x16x32_bf16 v[2:5], v[36:39], v[108:111], v[2:5]
	global_load_dwordx4 v[36:39], v[20:21], off offset:1152
	s_waitcnt vmcnt(7)
	v_mfma_f32_16x16x32_bf16 v[2:5], v[40:43], v[112:115], v[2:5]
	global_load_dwordx4 v[40:43], v[20:21], off offset:1216
	s_waitcnt vmcnt(7)
	v_mfma_f32_16x16x32_bf16 v[2:5], v[44:47], v[116:119], v[2:5]
	global_load_dwordx4 v[44:47], v[20:21], off offset:1280
	s_waitcnt vmcnt(7)
	v_mfma_f32_16x16x32_bf16 v[2:5], v[48:51], v[120:123], v[2:5]
	global_load_dwordx4 v[48:51], v[20:21], off offset:1344
	s_waitcnt vmcnt(7)
	v_mfma_f32_16x16x32_bf16 v[2:5], v[52:55], v[124:127], v[2:5]
	global_load_dwordx4 v[52:55], v[20:21], off offset:1408
	s_waitcnt vmcnt(7)
	v_mfma_f32_16x16x32_bf16 v[2:5], v[56:59], v[142:145], v[2:5]
	global_load_dwordx4 v[56:59], v[20:21], off offset:1472
	s_waitcnt vmcnt(7)
	v_mfma_f32_16x16x32_bf16 v[2:5], v[28:31], v[146:149], v[2:5]
	global_load_dwordx4 v[28:31], v[20:21], off offset:1536
	s_waitcnt vmcnt(7)
	v_mfma_f32_16x16x32_bf16 v[2:5], v[32:35], v[150:153], v[2:5]
	global_load_dwordx4 v[32:35], v[20:21], off offset:1600
	s_waitcnt vmcnt(7)
	v_mfma_f32_16x16x32_bf16 v[2:5], v[36:39], v[154:157], v[2:5]
	global_load_dwordx4 v[36:39], v[20:21], off offset:1664
	s_waitcnt vmcnt(7)
	v_mfma_f32_16x16x32_bf16 v[2:5], v[40:43], v[158:161], v[2:5]
	global_load_dwordx4 v[40:43], v[20:21], off offset:1728
	s_waitcnt vmcnt(7)
	v_mfma_f32_16x16x32_bf16 v[2:5], v[44:47], v[162:165], v[2:5]
	global_load_dwordx4 v[44:47], v[20:21], off offset:1792
	s_waitcnt vmcnt(7)
	v_mfma_f32_16x16x32_bf16 v[2:5], v[48:51], v[166:169], v[2:5]
	global_load_dwordx4 v[48:51], v[20:21], off offset:1856
	s_waitcnt vmcnt(7)
	v_mfma_f32_16x16x32_bf16 v[2:5], v[52:55], v[170:173], v[2:5]
	global_load_dwordx4 v[52:55], v[20:21], off offset:1920
	s_waitcnt vmcnt(7)
	v_mfma_f32_16x16x32_bf16 v[2:5], v[56:59], v[184:187], v[2:5]
	global_load_dwordx4 v[56:59], v[20:21], off offset:1984
	s_waitcnt vmcnt(7)
	v_mfma_f32_16x16x32_bf16 v[2:5], v[28:31], v[188:191], v[2:5]
	s_waitcnt vmcnt(6)
	v_mfma_f32_16x16x32_bf16 v[2:5], v[32:35], v[198:201], v[2:5]
	s_waitcnt vmcnt(5)
	v_mfma_f32_16x16x32_bf16 v[2:5], v[36:39], v[202:205], v[2:5]
	s_waitcnt vmcnt(4)
	v_mfma_f32_16x16x32_bf16 v[2:5], v[40:43], v[206:209], v[2:5]
	s_waitcnt vmcnt(3)
	v_mfma_f32_16x16x32_bf16 v[2:5], v[44:47], v[210:213], v[2:5]
	s_waitcnt vmcnt(2)
	v_mfma_f32_16x16x32_bf16 v[2:5], v[48:51], v[218:221], v[2:5]
	s_waitcnt vmcnt(1)
	v_mfma_f32_16x16x32_bf16 v[2:5], v[52:55], v[222:225], v[2:5]
	s_waitcnt vmcnt(0)
	v_mfma_f32_16x16x32_bf16 v[2:5], v[56:59], v[226:229], v[2:5]
	v_lshl_or_b32 v18, s3, 4, v22
	v_ashrrev_i32_e32 v19, 31, v18
	v_lshl_add_u64 v[20:21], v[18:19], 2, s[34:35]
	global_load_dword v13, v[20:21], off
	s_waitcnt vmcnt(0)
	v_fmamk_f32 v13, v13, 0x3a800000, v8
	v_mul_f32_e32 v17, 0x4b800000, v13
	v_cmp_gt_f32_e32 vcc, s8, v13
	s_nop 1
	v_cndmask_b32_e32 v13, v13, v17, vcc
	v_rsq_f32_e32 v13, v13
	s_nop 0
	v_mul_f32_e32 v17, 0x45800000, v13
	v_cndmask_b32_e32 v13, v13, v17, vcc
	v_fma_f32 v2, v2, v13, v1
	s_and_saveexec_b64 s[4:5], s[0:1]
	s_cbranch_execz .LBB0_445
; __device__ __forceinline__ float row_rs(const float* ss, int row) { return rsqrtf(ss[row] * (1.f / 1024.f) + EPS); }
; __device__ __forceinline__ void gates_phase(const Args& a) {
;     ...
;         for (int j = 0; j < 4; ++j) { const int row = r0 + 4 * g + j; float v = acc[j] * row_rs(PS1, row) + bias;
;             if (isf) v = fminf(v, 0.f) - log1pf(__expf(-fabsf(v)));
;             GATES[(size_t)row * 16 + c16] = v; }
	v_mul_f32_e64 v13, |v2|, s9
	v_exp_f32_e32 v13, v13
	v_max_f32_e32 v2, v2, v2
	v_min_f32_e32 v2, 0, v2
	v_add_f32_e32 v17, 1.0, v13
	v_add_f32_e32 v20, -1.0, v17
	v_sub_f32_e32 v21, v20, v17
	v_sub_f32_e32 v20, v13, v20
	v_add_f32_e32 v21, 1.0, v21
	v_add_f32_e32 v27, v20, v21
	v_frexp_mant_f32_e32 v28, v17
	v_cvt_f64_f32_e32 v[20:21], v17
	v_frexp_exp_i32_f64_e32 v20, v[20:21]
	v_cmp_gt_f32_e32 vcc, s10, v28
	s_nop 1
	v_subbrev_co_u32_e32 v34, vcc, 0, v20, vcc
	v_sub_u32_e32 v20, 0, v34
	v_ldexp_f32 v17, v17, v20
	v_ldexp_f32 v20, v27, v20
	v_add_f32_e32 v27, -1.0, v17
	v_add_f32_e32 v21, 1.0, v27
	v_sub_f32_e32 v21, v17, v21
	v_add_f32_e32 v28, v20, v21
	v_add_f32_e32 v21, 1.0, v17
	v_add_f32_e32 v29, -1.0, v21
	v_sub_f32_e32 v17, v17, v29
	v_add_f32_e32 v17, v20, v17
	v_add_f32_e32 v35, v21, v17
	v_rcp_f32_e32 v36, v35
	v_sub_f32_e32 v20, v35, v21
	v_add_f32_e32 v21, v27, v28
	v_sub_f32_e32 v17, v17, v20
	v_sub_f32_e32 v20, v21, v27
	v_mul_f32_e32 v37, v21, v36
	v_sub_f32_e32 v27, v28, v20
	v_mul_f32_e32 v28, v35, v37
	v_fma_f32 v30, v37, v35, -v28
	v_fmac_f32_e32 v30, v37, v17
	v_add_f32_e32 v20, v28, v30
	v_sub_f32_e32 v29, v21, v20
	v_pk_add_f32 v[32:33], v[20:21], v[28:29] neg_lo:[0,1] neg_hi:[0,1]
	v_mov_b32_e32 v31, v20
	v_pk_add_f32 v[20:21], v[32:33], v[30:31] neg_lo:[0,1] neg_hi:[0,1]
	v_cmp_neq_f32_e32 vcc, s12, v13
	v_add_f32_e32 v21, v27, v21
	v_add_f32_e32 v20, v20, v21
	v_add_f32_e32 v21, v29, v20
	v_mul_f32_e32 v27, v36, v21
	v_mul_f32_e32 v28, v35, v27
	v_fma_f32 v30, v27, v35, -v28
	v_fmac_f32_e32 v30, v27, v17
	v_sub_f32_e32 v17, v29, v21
	v_add_f32_e32 v17, v20, v17
	v_add_f32_e32 v20, v28, v30
	v_sub_f32_e32 v29, v21, v20
	v_pk_add_f32 v[32:33], v[20:21], v[28:29] neg_lo:[0,1] neg_hi:[0,1]
	v_mov_b32_e32 v31, v20
	v_pk_add_f32 v[20:21], v[32:33], v[30:31] neg_lo:[0,1] neg_hi:[0,1]
	s_nop 0
	v_add_f32_e32 v17, v17, v21
	v_add_f32_e32 v17, v20, v17
	v_add_f32_e32 v21, v37, v27
	v_add_f32_e32 v17, v29, v17
	v_sub_f32_e32 v20, v21, v37
	v_mul_f32_e32 v17, v36, v17
	v_sub_f32_e32 v20, v27, v20
	v_add_f32_e32 v27, v20, v17
	v_add_f32_e32 v28, v21, v27
	v_cvt_f32_i32_e32 v20, v34
	v_mul_f32_e32 v30, v28, v28
	v_sub_f32_e32 v21, v28, v21
	v_fmamk_f32 v17, v30, 0x3e9b6dac, v23
	v_sub_f32_e32 v21, v27, v21
	v_fmaak_f32 v17, v30, v17, 0x3f2aaada
	v_ldexp_f32 v27, v21, 1
	v_mul_f32_e32 v21, v28, v30
	v_pk_mul_f32 v[30:31], v[20:21], v[16:17]
	v_ldexp_f32 v29, v28, 1
	v_fma_f32 v28, v20, s11, -v30
	v_fmac_f32_e32 v28, 0xb102e308, v20
	v_pk_add_f32 v[20:21], v[30:31], v[28:29]
	v_mov_b32_e32 v32, v30
	v_sub_f32_e32 v17, v21, v29
	v_sub_f32_e32 v17, v31, v17
	v_add_f32_e32 v33, v27, v17
	v_pk_add_f32 v[30:31], v[20:21], v[30:31] neg_lo:[0,1] neg_hi:[0,1]
	v_pk_add_f32 v[34:35], v[20:21], v[32:33]
	v_mov_b32_e32 v29, v20
	v_mov_b32_e32 v31, v35
	v_pk_add_f32 v[36:37], v[28:29], v[30:31] neg_lo:[0,1] neg_hi:[0,1]
	v_pk_add_f32 v[28:29], v[28:29], v[30:31]
	v_mov_b32_e32 v32, v33
	v_pk_add_f32 v[30:31], v[28:29], v[20:21] op_sel:[1,0] op_sel_hi:[0,1] neg_lo:[0,1] neg_hi:[0,1]
	v_pk_add_f32 v[38:39], v[34:35], v[30:31] op_sel_hi:[1,0] neg_lo:[0,1] neg_hi:[0,1]
	v_mov_b32_e32 v34, v35
	v_mov_b32_e32 v35, v29
	v_pk_mov_b32 v[30:31], v[20:21], v[30:31] op_sel:[1,0]
	v_mov_b32_e32 v33, v20
	v_pk_add_f32 v[30:31], v[34:35], v[30:31] neg_lo:[0,1] neg_hi:[0,1]
	v_mov_b32_e32 v38, v36
	v_pk_add_f32 v[20:21], v[32:33], v[30:31] neg_lo:[0,1] neg_hi:[0,1]
	v_mov_b32_e32 v37, v29
	v_pk_add_f32 v[30:31], v[38:39], v[20:21]
	s_nop 0
	v_pk_add_f32 v[32:33], v[30:31], v[30:31] op_sel:[0,1] op_sel_hi:[1,0]
	s_nop 0
	v_pk_add_f32 v[28:29], v[28:29], v[32:33] op_sel:[1,0] op_sel_hi:[0,1]
	v_mov_b32_e32 v31, v28
	v_pk_add_f32 v[34:35], v[30:31], v[36:37] neg_lo:[0,1] neg_hi:[0,1]
	v_mov_b32_e32 v21, v32
	v_sub_f32_e32 v17, v30, v34
	v_pk_add_f32 v[20:21], v[20:21], v[34:35] neg_lo:[0,1] neg_hi:[0,1]
	v_sub_f32_e32 v17, v36, v17
	v_add_f32_e32 v17, v20, v17
	v_add_f32_e32 v17, v17, v21
	v_add_f32_e32 v17, v28, v17
	v_cndmask_b32_e32 v17, v24, v17, vcc
	v_cmp_ngt_f32_e32 vcc, -1.0, v13
	s_nop 1
	v_cndmask_b32_e32 v17, v25, v17, vcc
	v_cmp_neq_f32_e32 vcc, -1.0, v13
	s_nop 1
	v_cndmask_b32_e32 v17, v26, v17, vcc
	v_cmp_lt_f32_e64 vcc, |v13|, s13
	s_nop 1
	v_cndmask_b32_e32 v13, v17, v13, vcc
	v_sub_f32_e32 v2, v2, v13

; #define PG8_LDA(dst, b, h) do { _Pragma("unroll") for (int m = 0; m < 4; ++m) _Pragma("unroll") for (int k = 0; k < 2; ++k) dst[m][k] = *(const LAS bf16x8*)(lds + PG8_SA(b, h) + aoff + m * 2048 + k * 1024); } while (0)
; template <class Epi, class Sched>
; __device__ __forceinline__ void gemm_phase(LAS unsigned char* lds, const int lda, const int ldb, const int K, const Sched& S, const Epi& E) {
;     ...
;     Unit cur, nxt; int ui = 0;
;     if (!S.next(0, cur)) return;
;     f32x4 acc[2][2][4][2];
; #pragma unroll
;     for (int a = 0; a < 2; ++a)
; #pragma unroll
;         for (int b = 0; b < 2; ++b)
; #pragma unroll
;             for (int m = 0; m < 4; ++m)
; #pragma unroll
;                 for (int n = 0; n < 2; ++n) acc[a][b][m][n] = (f32x4){0.f, 0.f, 0.f, 0.f};
;     bf16x8 At[4][2], B0[2][2], B1[2][2];
;     float rsv[8];
; #pragma unroll
;     for (int i = 0; i < 8; ++i) rsv[i] = 0.f;
;     const char* cA = cur.A; const char* cB = cur.B;
;     PG8_STAGE(PG8_SB(0, 0), cB, voffB); PG8_STAGE(PG8_SB(0, 1), cB + hstepB, voffB); PG8_STAGE(PG8_SA(0, 0), cA, voffA); PG8_STAGE(PG8_SA(0, 1), cA + hstepA, voffA);
;     if (wr == 1) PG8_BAR;
;     PG8_WAIT_V(2); PG8_BAR;
;     PG8_STAGE(PG8_SB(1, 0), cB + kstep, voffB); PG8_STAGE(PG8_SA(1, 0), cA + kstep, voffA); PG8_STAGE(PG8_SB(1, 1), cB + hstepB + kstep, voffB);
;     PG8_WAIT_V(6); PG8_BAR;
;     for (;;) {
;         const bool has_next = S.next(ui + 1, nxt);
;         const char* nA = has_next ? nxt.A : cA; const char* nB = has_next ? nxt.B : cB;
;         for (int t = 0; t < nt; t += 2) {
;             const bool last = (t == nt - 2);
;             const char* a1 = cA + (size_t)(t + 1) * kstep;
;             const char* a2 = last ? nA : cA + (size_t)(t + 2) * kstep; const char* b2 = last ? nB : cB + (size_t)(t + 2) * kstep;
;             const char* a3 = a2 + kstep; const char* b3 = b2 + kstep;
;             PG8_LDB(B0, 0, 0); PG8_LDB(B1, 0, 1); PG8_SCHED; PG8_LDA(At, 0, 0); PG8_STAGE(PG8_SA(1, 1), a1 + hstepA, voffA);
;             PG8_WAIT_V(8); PG8_WAIT_L(0); PG8_BAR; PG8_MMA(0, 0, At, B0); PG8_MMA(0, 1, At, B1); PG8_BAR; PG8_SCHED;
;             PG8_LDA(At, 0, 1); PG8_STAGE(PG8_SB(0, 0), b2, voffB); PG8_STAGE(PG8_SB(0, 1), b2 + hstepB, voffB); PG8_STAGE(PG8_SA(0, 0), a2, voffA);
;             PG8_WAIT_V(8); PG8_WAIT_L(0); PG8_BAR; PG8_MMA(1, 0, At, B0); PG8_MMA(1, 1, At, B1); PG8_BAR; PG8_SCHED;
.LBB0_955:
	s_add_u32 s24, s24, 0x40080
	s_addc_u32 s25, s25, 0
	s_add_u32 s15, s26, 0x100
	s_addc_u32 s17, s27, 0
	s_mov_b32 s23, -2
	s_waitcnt lgkmcnt(0)
	v_add_u32_e32 v192, 0x80, v156
	v_add_u32_e32 v193, 0x80, v160
	v_add_u32_e32 v220, 0x80, v154
	v_add_u32_e32 v221, 0x80, v158
	ds_read_b128 v[130:133], v188
	ds_read_b128 v[134:137], v188 offset:1024
	ds_read_b128 v[138:141], v188 offset:2048
	ds_read_b128 v[142:145], v188 offset:3072
	ds_read_b128 v[146:149], v189
	ds_read_b128 v[150:153], v189 offset:1024
	ds_read_b128 v[170:173], v189 offset:2048
	ds_read_b128 v[174:177], v189 offset:3072
	s_add_u32 s26, s24, 0xfffc0080
	s_addc_u32 s27, s25, -1
	s_cmp_eq_u32 s23, 12
	s_cselect_b32 s29, s19, s27
	s_cselect_b32 s28, s18, s26
	s_cselect_b32 s27, s21, s17
	s_cselect_b32 s26, s20, s15
	s_add_i32 m0, s33, 0xc000
	ds_read_b128 v[178:181], v190
	ds_read_b128 v[182:185], v190 offset:1024
	ds_read_b128 v[196:199], v190 offset:2048
	ds_read_b128 v[200:203], v190 offset:3072
	ds_read_b128 v[204:207], v190 offset:4096
	ds_read_b128 v[208:211], v190 offset:5120
	ds_read_b128 v[212:215], v190 offset:6144
	ds_read_b128 v[216:219], v190 offset:7168
	global_load_lds_dwordx4 v162, s[24:25]
	s_add_i32 m0, s33, 0xe000
	s_nop 0
	global_load_lds_dwordx4 v164, s[24:25]
	s_waitcnt vmcnt(8)
	s_waitcnt lgkmcnt(0)
	s_barrier
	s_setprio 1
	s_waitcnt lgkmcnt(0)
	v_mfma_f32_16x16x32_bf16 v[126:129], v[130:133], v[178:181], 0
	v_mfma_f32_16x16x32_bf16 v[122:125], v[138:141], v[178:181], 0
	v_mfma_f32_16x16x32_bf16 v[110:113], v[130:133], v[196:199], 0
	v_mfma_f32_16x16x32_bf16 v[106:109], v[138:141], v[196:199], 0
	v_mfma_f32_16x16x32_bf16 v[94:97], v[130:133], v[204:207], 0
	v_mfma_f32_16x16x32_bf16 v[90:93], v[138:141], v[204:207], 0
	v_mfma_f32_16x16x32_bf16 v[78:81], v[130:133], v[212:215], 0
	v_mfma_f32_16x16x32_bf16 v[74:77], v[138:141], v[212:215], 0
	v_mfma_f32_16x16x32_bf16 v[126:129], v[134:137], v[182:185], v[126:129]
	v_mfma_f32_16x16x32_bf16 v[122:125], v[142:145], v[182:185], v[122:125]
	v_mfma_f32_16x16x32_bf16 v[110:113], v[134:137], v[200:203], v[110:113]
	v_mfma_f32_16x16x32_bf16 v[106:109], v[142:145], v[200:203], v[106:109]
	v_mfma_f32_16x16x32_bf16 v[94:97], v[134:137], v[208:211], v[94:97]
	v_mfma_f32_16x16x32_bf16 v[90:93], v[142:145], v[208:211], v[90:93]
	v_mfma_f32_16x16x32_bf16 v[78:81], v[134:137], v[216:219], v[78:81]
	v_mfma_f32_16x16x32_bf16 v[74:77], v[142:145], v[216:219], v[74:77]
	s_setprio 0
	s_setprio 1
	v_mfma_f32_16x16x32_bf16 v[118:121], v[146:149], v[178:181], 0
	v_mfma_f32_16x16x32_bf16 v[114:117], v[170:173], v[178:181], 0
	v_mfma_f32_16x16x32_bf16 v[102:105], v[146:149], v[196:199], 0
	v_mfma_f32_16x16x32_bf16 v[98:101], v[170:173], v[196:199], 0
	v_mfma_f32_16x16x32_bf16 v[86:89], v[146:149], v[204:207], 0
	v_mfma_f32_16x16x32_bf16 v[82:85], v[170:173], v[204:207], 0
	v_mfma_f32_16x16x32_bf16 v[70:73], v[146:149], v[212:215], 0
	v_mfma_f32_16x16x32_bf16 v[66:69], v[170:173], v[212:215], 0
	v_mfma_f32_16x16x32_bf16 v[118:121], v[150:153], v[182:185], v[118:121]
	v_mfma_f32_16x16x32_bf16 v[114:117], v[174:177], v[182:185], v[114:117]
	v_mfma_f32_16x16x32_bf16 v[102:105], v[150:153], v[200:203], v[102:105]
	v_mfma_f32_16x16x32_bf16 v[98:101], v[174:177], v[200:203], v[98:101]
	v_mfma_f32_16x16x32_bf16 v[86:89], v[150:153], v[208:211], v[86:89]
	v_mfma_f32_16x16x32_bf16 v[82:85], v[174:177], v[208:211], v[82:85]
	v_mfma_f32_16x16x32_bf16 v[70:73], v[150:153], v[216:219], v[70:73]
	v_mfma_f32_16x16x32_bf16 v[66:69], v[174:177], v[216:219], v[66:69]
	s_setprio 0
	s_barrier
	s_add_i32 s51, s48, s31
	s_mov_b32 m0, s51
	ds_read_b128 v[178:181], v190 offset:16384
	ds_read_b128 v[182:185], v190 offset:17408
	ds_read_b128 v[196:199], v190 offset:18432
	ds_read_b128 v[200:203], v190 offset:19456
	ds_read_b128 v[204:207], v190 offset:20480
	ds_read_b128 v[208:211], v190 offset:21504
	ds_read_b128 v[212:215], v190 offset:22528
	ds_read_b128 v[216:219], v190 offset:23552
	global_load_lds_dwordx4 v156, s[26:27]
	s_add_i32 m0, s51, 0x2000
	s_add_u32 s62, s26, 0x40000
	s_mov_b64 s[98:99], s[26:27]
	s_addc_u32 s63, s27, 0
	s_add_i32 s51, s49, s31
	global_load_lds_dwordx4 v160, s[26:27]
	s_mov_b32 m0, s51
	s_mov_b64 s[100:101], s[28:29]
	global_load_lds_dwordx4 v156, s[62:63]
	s_add_i32 m0, s51, 0x2000
	s_nop 0
	global_load_lds_dwordx4 v160, s[62:63]
	s_mov_b32 m0, s33
	s_nop 0
	global_load_lds_dwordx4 v154, s[28:29]
	s_mov_b32 m0, s34
	s_nop 0
	global_load_lds_dwordx4 v158, s[28:29]
	s_waitcnt vmcnt(8)
	s_waitcnt lgkmcnt(0)
	s_barrier
	s_setprio 1
	s_waitcnt lgkmcnt(0)
	v_mfma_f32_16x16x32_bf16 v[62:65], v[130:133], v[178:181], 0
	v_mfma_f32_16x16x32_bf16 v[58:61], v[138:141], v[178:181], 0
	v_mfma_f32_16x16x32_bf16 v[46:49], v[130:133], v[196:199], 0
	v_mfma_f32_16x16x32_bf16 v[42:45], v[138:141], v[196:199], 0
	v_mfma_f32_16x16x32_bf16 v[30:33], v[130:133], v[204:207], 0
	v_mfma_f32_16x16x32_bf16 v[26:29], v[138:141], v[204:207], 0
	v_mfma_f32_16x16x32_bf16 v[14:17], v[130:133], v[212:215], 0
	v_mfma_f32_16x16x32_bf16 v[10:13], v[138:141], v[212:215], 0
	v_mfma_f32_16x16x32_bf16 v[62:65], v[134:137], v[182:185], v[62:65]
	v_mfma_f32_16x16x32_bf16 v[58:61], v[142:145], v[182:185], v[58:61]
	v_mfma_f32_16x16x32_bf16 v[46:49], v[134:137], v[200:203], v[46:49]
	v_mfma_f32_16x16x32_bf16 v[42:45], v[142:145], v[200:203], v[42:45]
	v_mfma_f32_16x16x32_bf16 v[30:33], v[134:137], v[208:211], v[30:33]
	v_mfma_f32_16x16x32_bf16 v[26:29], v[142:145], v[208:211], v[26:29]
	v_mfma_f32_16x16x32_bf16 v[14:17], v[134:137], v[216:219], v[14:17]
	v_mfma_f32_16x16x32_bf16 v[10:13], v[142:145], v[216:219], v[10:13]
	s_setprio 0
	s_setprio 1
	v_mfma_f32_16x16x32_bf16 v[54:57], v[146:149], v[178:181], 0
	v_mfma_f32_16x16x32_bf16 v[50:53], v[170:173], v[178:181], 0
	v_mfma_f32_16x16x32_bf16 v[38:41], v[146:149], v[196:199], 0
	v_mfma_f32_16x16x32_bf16 v[34:37], v[170:173], v[196:199], 0
	v_mfma_f32_16x16x32_bf16 v[22:25], v[146:149], v[204:207], 0
	v_mfma_f32_16x16x32_bf16 v[18:21], v[170:173], v[204:207], 0
	v_mfma_f32_16x16x32_bf16 v[6:9], v[146:149], v[212:215], 0
	v_mfma_f32_16x16x32_bf16 v[2:5], v[170:173], v[212:215], 0
	v_mfma_f32_16x16x32_bf16 v[54:57], v[150:153], v[182:185], v[54:57]
	v_mfma_f32_16x16x32_bf16 v[50:53], v[174:177], v[182:185], v[50:53]
	v_mfma_f32_16x16x32_bf16 v[38:41], v[150:153], v[200:203], v[38:41]
	v_mfma_f32_16x16x32_bf16 v[34:37], v[174:177], v[200:203], v[34:37]
	v_mfma_f32_16x16x32_bf16 v[22:25], v[150:153], v[208:211], v[22:25]
	v_mfma_f32_16x16x32_bf16 v[18:21], v[174:177], v[208:211], v[18:21]
	v_mfma_f32_16x16x32_bf16 v[6:9], v[150:153], v[216:219], v[6:9]
	v_mfma_f32_16x16x32_bf16 v[2:5], v[174:177], v[216:219], v[2:5]
	s_setprio 0
	s_barrier
	s_branch .Lpeel5_join

; #define PG8_STAGE(bufoff, gbase, voff) do { _Pragma("unroll") for (int _i = 0; _i < 2; ++_i) \
;         __builtin_amdgcn_global_load_lds((const unsigned*)((const char*)(gbase) + (voff)[_i]), (LAS unsigned*)(lds + (bufoff) + ldsw + _i * 8192), 16, 0, 0); } while (0)
; #define PG8_LDA(dst, b, h) do { _Pragma("unroll") for (int m = 0; m < 4; ++m) _Pragma("unroll") for (int k = 0; k < 2; ++k) dst[m][k] = *(const LAS bf16x8*)(lds + PG8_SA(b, h) + aoff + m * 2048 + k * 1024); } while (0)
; #define PG8_LDB(dst, b, h) do { _Pragma("unroll") for (int n = 0; n < 2; ++n) _Pragma("unroll") for (int k = 0; k < 2; ++k) dst[n][k] = *(const LAS bf16x8*)(lds + PG8_SB(b, h) + boff + n * 2048 + k * 1024); } while (0)
; #define PG8_MMA(ai, bj, At, Bt) do { __builtin_amdgcn_s_setprio(1); _Pragma("unroll") for (int m = 0; m < 4; ++m) _Pragma("unroll") for (int n = 0; n < 2; ++n) _Pragma("unroll") for (int k = 0; k < 2; ++k) \
;         acc[ai][bj][m][n] = __builtin_amdgcn_mfma_f32_16x16x32_bf16(Bt[n][k], At[m][k], acc[ai][bj][m][n], 0, 0, 0); __builtin_amdgcn_s_setprio(0); } while (0)
; #define PG8_WAIT_V(n) asm volatile("s_waitcnt vmcnt(" #n ")" ::: "memory")
; #define PG8_WAIT_L(n) asm volatile("s_waitcnt lgkmcnt(" #n ")" ::: "memory")
; #define PG8_BAR __builtin_amdgcn_s_barrier()
; #define PG8_SCHED __builtin_amdgcn_sched_barrier(0)
; template <class Epi, class Sched>
; __device__ __forceinline__ void gemm_phase(LAS unsigned char* lds, const int lda, const int ldb, const int K, const Sched& S, const Epi& E) {
;     ...
;             PG8_LDB(B0, 1, 0); PG8_LDB(B1, 1, 1); PG8_SCHED; PG8_LDA(At, 1, 0); PG8_STAGE(PG8_SA(0, 1), a2 + hstepA, voffA);
;             PG8_WAIT_V(8); PG8_WAIT_L(0); PG8_BAR; PG8_MMA(0, 0, At, B0); PG8_MMA(0, 1, At, B1); PG8_BAR; PG8_SCHED;
;             PG8_LDA(At, 1, 1); PG8_STAGE(PG8_SB(1, 0), b3, voffB); PG8_STAGE(PG8_SB(1, 1), b3 + hstepB, voffB); PG8_STAGE(PG8_SA(1, 0), a3, voffA);
;             PG8_WAIT_V(8); PG8_WAIT_L(0); PG8_BAR;
;             if (last) E.pre(cur, wr, fr, rsv);
;             PG8_MMA(1, 0, At, B0); PG8_MMA(1, 1, At, B1); PG8_BAR; PG8_SCHED;
;         }
;         if (wr == 0) PG8_BAR;
.Lpeel5_join:
	s_add_i32 s51, 0, 0x18000
	s_add_i32 s62, 0, 0x1c000
	v_add_u32_e32 v142, s51, v186
	v_add_u32_e32 v174, s62, v186
	ds_read_b128 v[130:133], v142
	ds_read_b128 v[134:137], v142 offset:1024
	ds_read_b128 v[138:141], v142 offset:2048
	ds_read_b128 v[142:145], v142 offset:3072
	ds_read_b128 v[146:149], v174
	ds_read_b128 v[150:153], v174 offset:1024
	ds_read_b128 v[170:173], v174 offset:2048
	ds_read_b128 v[174:177], v174 offset:3072
	s_add_u32 s28, s28, 0x40000
	s_addc_u32 s29, s29, 0
	s_mov_b32 m0, s35
	ds_read_b128 v[178:181], v190 offset:32768
	ds_read_b128 v[182:185], v190 offset:33792
	ds_read_b128 v[196:199], v190 offset:34816
	ds_read_b128 v[200:203], v190 offset:35840
	ds_read_b128 v[204:207], v190 offset:36864
	ds_read_b128 v[208:211], v190 offset:37888
	ds_read_b128 v[212:215], v190 offset:38912
	ds_read_b128 v[216:219], v190 offset:39936
	global_load_lds_dwordx4 v154, s[28:29]
	s_mov_b32 m0, s38
	s_nop 0
	global_load_lds_dwordx4 v158, s[28:29]
	s_waitcnt vmcnt(8)
	s_waitcnt lgkmcnt(0)
	s_barrier
	s_setprio 1
	s_waitcnt lgkmcnt(0)
	v_mfma_f32_16x16x32_bf16 v[126:129], v[130:133], v[178:181], v[126:129]
	v_mfma_f32_16x16x32_bf16 v[122:125], v[138:141], v[178:181], v[122:125]
	v_mfma_f32_16x16x32_bf16 v[110:113], v[130:133], v[196:199], v[110:113]
	v_mfma_f32_16x16x32_bf16 v[106:109], v[138:141], v[196:199], v[106:109]
	v_mfma_f32_16x16x32_bf16 v[94:97], v[130:133], v[204:207], v[94:97]
	v_mfma_f32_16x16x32_bf16 v[90:93], v[138:141], v[204:207], v[90:93]
	v_mfma_f32_16x16x32_bf16 v[78:81], v[130:133], v[212:215], v[78:81]
	v_mfma_f32_16x16x32_bf16 v[74:77], v[138:141], v[212:215], v[74:77]
	v_mfma_f32_16x16x32_bf16 v[126:129], v[134:137], v[182:185], v[126:129]
	v_mfma_f32_16x16x32_bf16 v[122:125], v[142:145], v[182:185], v[122:125]
	v_mfma_f32_16x16x32_bf16 v[110:113], v[134:137], v[200:203], v[110:113]
	v_mfma_f32_16x16x32_bf16 v[106:109], v[142:145], v[200:203], v[106:109]
	v_mfma_f32_16x16x32_bf16 v[94:97], v[134:137], v[208:211], v[94:97]
	v_mfma_f32_16x16x32_bf16 v[90:93], v[142:145], v[208:211], v[90:93]
	v_mfma_f32_16x16x32_bf16 v[78:81], v[134:137], v[216:219], v[78:81]
	v_mfma_f32_16x16x32_bf16 v[74:77], v[142:145], v[216:219], v[74:77]
	s_setprio 0
	s_setprio 1
	v_mfma_f32_16x16x32_bf16 v[118:121], v[146:149], v[178:181], v[118:121]
	v_mfma_f32_16x16x32_bf16 v[114:117], v[170:173], v[178:181], v[114:117]
	v_mfma_f32_16x16x32_bf16 v[102:105], v[146:149], v[196:199], v[102:105]
	v_mfma_f32_16x16x32_bf16 v[98:101], v[170:173], v[196:199], v[98:101]
	v_mfma_f32_16x16x32_bf16 v[86:89], v[146:149], v[204:207], v[86:89]
	v_mfma_f32_16x16x32_bf16 v[82:85], v[170:173], v[204:207], v[82:85]
	v_mfma_f32_16x16x32_bf16 v[70:73], v[146:149], v[212:215], v[70:73]
	v_mfma_f32_16x16x32_bf16 v[66:69], v[170:173], v[212:215], v[66:69]
	v_mfma_f32_16x16x32_bf16 v[118:121], v[150:153], v[182:185], v[118:121]
	v_mfma_f32_16x16x32_bf16 v[114:117], v[174:177], v[182:185], v[114:117]
	v_mfma_f32_16x16x32_bf16 v[102:105], v[150:153], v[200:203], v[102:105]
	v_mfma_f32_16x16x32_bf16 v[98:101], v[174:177], v[200:203], v[98:101]
	v_mfma_f32_16x16x32_bf16 v[86:89], v[150:153], v[208:211], v[86:89]
	v_mfma_f32_16x16x32_bf16 v[82:85], v[174:177], v[208:211], v[82:85]
	v_mfma_f32_16x16x32_bf16 v[70:73], v[150:153], v[216:219], v[70:73]
	v_mfma_f32_16x16x32_bf16 v[66:69], v[174:177], v[216:219], v[66:69]
	s_setprio 0
	s_barrier
	s_add_i32 s28, s51, s31
	s_mov_b32 m0, s28
	ds_read_b128 v[178:181], v190 offset:49152
	ds_read_b128 v[182:185], v190 offset:50176
	ds_read_b128 v[196:199], v190 offset:51200
	ds_read_b128 v[200:203], v190 offset:52224
	ds_read_b128 v[204:207], v190 offset:53248
	ds_read_b128 v[208:211], v190 offset:54272
	ds_read_b128 v[212:215], v190 offset:55296
	ds_read_b128 v[216:219], v190 offset:56320
	global_load_lds_dwordx4 v192, s[26:27]
	s_add_i32 m0, s28, 0x2000
	s_add_u32 s26, s26, 0x40080
	s_addc_u32 s27, s27, 0
	s_add_i32 s28, s62, s31
	global_load_lds_dwordx4 v193, s[98:99]
	s_mov_b32 m0, s28
	s_nop 0
	global_load_lds_dwordx4 v156, s[26:27]
	s_add_i32 m0, s28, 0x2000
	s_nop 0
	global_load_lds_dwordx4 v160, s[26:27]
	s_mov_b32 m0, s41
	s_nop 0
	global_load_lds_dwordx4 v220, s[100:101]
	s_mov_b32 m0, s42
	s_nop 0
	global_load_lds_dwordx4 v221, s[100:101]
	s_waitcnt vmcnt(8)
	s_waitcnt lgkmcnt(0)
	s_barrier
	s_setprio 1
	s_waitcnt lgkmcnt(0)
	v_mfma_f32_16x16x32_bf16 v[62:65], v[130:133], v[178:181], v[62:65]
	v_mfma_f32_16x16x32_bf16 v[58:61], v[138:141], v[178:181], v[58:61]
	v_mfma_f32_16x16x32_bf16 v[46:49], v[130:133], v[196:199], v[46:49]
	v_mfma_f32_16x16x32_bf16 v[42:45], v[138:141], v[196:199], v[42:45]
	v_mfma_f32_16x16x32_bf16 v[30:33], v[130:133], v[204:207], v[30:33]
	v_mfma_f32_16x16x32_bf16 v[26:29], v[138:141], v[204:207], v[26:29]
	v_mfma_f32_16x16x32_bf16 v[14:17], v[130:133], v[212:215], v[14:17]
	v_mfma_f32_16x16x32_bf16 v[10:13], v[138:141], v[212:215], v[10:13]
	v_mfma_f32_16x16x32_bf16 v[62:65], v[134:137], v[182:185], v[62:65]
	v_mfma_f32_16x16x32_bf16 v[58:61], v[142:145], v[182:185], v[58:61]
	v_mfma_f32_16x16x32_bf16 v[46:49], v[134:137], v[200:203], v[46:49]
	v_mfma_f32_16x16x32_bf16 v[42:45], v[142:145], v[200:203], v[42:45]
	v_mfma_f32_16x16x32_bf16 v[30:33], v[134:137], v[208:211], v[30:33]
	v_mfma_f32_16x16x32_bf16 v[26:29], v[142:145], v[208:211], v[26:29]
	v_mfma_f32_16x16x32_bf16 v[14:17], v[134:137], v[216:219], v[14:17]
	v_mfma_f32_16x16x32_bf16 v[10:13], v[142:145], v[216:219], v[10:13]
	s_setprio 0
	s_setprio 1
	v_mfma_f32_16x16x32_bf16 v[54:57], v[146:149], v[178:181], v[54:57]
	v_mfma_f32_16x16x32_bf16 v[50:53], v[170:173], v[178:181], v[50:53]
	v_mfma_f32_16x16x32_bf16 v[38:41], v[146:149], v[196:199], v[38:41]
	v_mfma_f32_16x16x32_bf16 v[34:37], v[170:173], v[196:199], v[34:37]
	v_mfma_f32_16x16x32_bf16 v[22:25], v[146:149], v[204:207], v[22:25]
	v_mfma_f32_16x16x32_bf16 v[18:21], v[170:173], v[204:207], v[18:21]
	v_mfma_f32_16x16x32_bf16 v[6:9], v[146:149], v[212:215], v[6:9]
	v_mfma_f32_16x16x32_bf16 v[2:5], v[170:173], v[212:215], v[2:5]
	v_mfma_f32_16x16x32_bf16 v[54:57], v[150:153], v[182:185], v[54:57]
	v_mfma_f32_16x16x32_bf16 v[50:53], v[174:177], v[182:185], v[50:53]
	v_mfma_f32_16x16x32_bf16 v[38:41], v[150:153], v[200:203], v[38:41]
	v_mfma_f32_16x16x32_bf16 v[34:37], v[174:177], v[200:203], v[34:37]
	v_mfma_f32_16x16x32_bf16 v[22:25], v[150:153], v[208:211], v[22:25]
	v_mfma_f32_16x16x32_bf16 v[18:21], v[174:177], v[208:211], v[18:21]
	v_mfma_f32_16x16x32_bf16 v[6:9], v[150:153], v[216:219], v[6:9]
	v_mfma_f32_16x16x32_bf16 v[2:5], v[174:177], v[216:219], v[2:5]
	s_setprio 0
	s_barrier
	s_add_i32 s23, s23, 2
	s_add_u32 s24, s24, 0x100
	s_addc_u32 s25, s25, 0
	s_add_u32 s15, s15, 0x100
	s_addc_u32 s17, s17, 0
	s_cmp_gt_u32 s23, 13
	s_cbranch_scc0 .LBB0_956
	s_and_b64 vcc, exec, s[12:13]
	s_cbranch_vccz .LBB0_959
	s_barrier

; #define PG8_STAGE(bufoff, gbase, voff) do { _Pragma("unroll") for (int _i = 0; _i < 2; ++_i) \
;         __builtin_amdgcn_global_load_lds((const unsigned*)((const char*)(gbase) + (voff)[_i]), (LAS unsigned*)(lds + (bufoff) + ldsw + _i * 8192), 16, 0, 0); } while (0)
; #define PG8_LDA(dst, b, h) do { _Pragma("unroll") for (int m = 0; m < 4; ++m) _Pragma("unroll") for (int k = 0; k < 2; ++k) dst[m][k] = *(const LAS bf16x8*)(lds + PG8_SA(b, h) + aoff + m * 2048 + k * 1024); } while (0)
; template <class Epi, class Sched>
; __device__ __forceinline__ void gemm_phase(LAS unsigned char* lds, const int lda, const int ldb, const int K, const Sched& S, const Epi& E) {
;     ...
;     Unit cur, nxt; int ui = 0;
;     if (!S.next(0, cur)) return;
;     f32x4 acc[2][2][4][2];
; #pragma unroll
;     for (int a = 0; a < 2; ++a)
; #pragma unroll
;         for (int b = 0; b < 2; ++b)
; #pragma unroll
;             for (int m = 0; m < 4; ++m)
; #pragma unroll
;                 for (int n = 0; n < 2; ++n) acc[a][b][m][n] = (f32x4){0.f, 0.f, 0.f, 0.f};
;     bf16x8 At[4][2], B0[2][2], B1[2][2];
;     float rsv[8];
; #pragma unroll
;     for (int i = 0; i < 8; ++i) rsv[i] = 0.f;
;     const char* cA = cur.A; const char* cB = cur.B;
;     PG8_STAGE(PG8_SB(0, 0), cB, voffB); PG8_STAGE(PG8_SB(0, 1), cB + hstepB, voffB); PG8_STAGE(PG8_SA(0, 0), cA, voffA); PG8_STAGE(PG8_SA(0, 1), cA + hstepA, voffA);
;     if (wr == 1) PG8_BAR;
;     PG8_WAIT_V(2); PG8_BAR;
;     PG8_STAGE(PG8_SB(1, 0), cB + kstep, voffB); PG8_STAGE(PG8_SA(1, 0), cA + kstep, voffA); PG8_STAGE(PG8_SB(1, 1), cB + hstepB + kstep, voffB);
;     PG8_WAIT_V(6); PG8_BAR;
;     for (;;) {
;         const bool has_next = S.next(ui + 1, nxt);
;         const char* nA = has_next ? nxt.A : cA; const char* nB = has_next ? nxt.B : cB;
;         for (int t = 0; t < nt; t += 2) {
;             const bool last = (t == nt - 2);
;             const char* a1 = cA + (size_t)(t + 1) * kstep;
;             const char* a2 = last ? nA : cA + (size_t)(t + 2) * kstep; const char* b2 = last ? nB : cB + (size_t)(t + 2) * kstep;
;             const char* a3 = a2 + kstep; const char* b3 = b2 + kstep;
;             PG8_LDB(B0, 0, 0); PG8_LDB(B1, 0, 1); PG8_SCHED; PG8_LDA(At, 0, 0); PG8_STAGE(PG8_SA(1, 1), a1 + hstepA, voffA);
;             PG8_WAIT_V(8); PG8_WAIT_L(0); PG8_BAR; PG8_MMA(0, 0, At, B0); PG8_MMA(0, 1, At, B1); PG8_BAR; PG8_SCHED;
.LBB0_1052:
	s_lshl_b32 s20, s20, 8
	s_ashr_i32 s21, s20, 31
	s_add_u32 s22, s22, 0x40080
	s_addc_u32 s23, s23, 0
	s_add_u32 s13, s24, 0x100
	v_lshl_add_u64 v[214:215], s[20:21], 2, v[204:205]
	s_addc_u32 s15, s25, 0
	s_mov_b32 s21, -2
	v_add_u32_e32 v230, 0x80, v200
	v_add_u32_e32 v231, 0x80, v196
	v_add_u32_e32 v232, 0x80, v202
	v_add_u32_e32 v233, 0x80, v198
	s_add_u32 s24, s22, 0xfffc0080
	s_addc_u32 s25, s23, -1
	s_cmp_eq_u32 s21, 12
	s_cselect_b32 s29, s17, s25
	s_cselect_b32 s28, s16, s24
	s_cselect_b32 s31, s19, s15
	s_cselect_b32 s30, s18, s13
	s_add_i32 s70, s50, s36
	ds_read_b128 v[130:133], v217
	ds_read_b128 v[134:137], v217 offset:1024
	ds_read_b128 v[138:141], v217 offset:2048
	ds_read_b128 v[142:145], v217 offset:3072
	ds_read_b128 v[146:149], v218
	ds_read_b128 v[150:153], v218 offset:1024
	ds_read_b128 v[154:157], v218 offset:2048
	ds_read_b128 v[158:161], v218 offset:3072
	s_add_i32 m0, s39, 0xc000
	s_add_i32 s69, s39, 0xe000
	s_add_i32 s71, s70, 0x2000
	s_add_u32 s34, s30, 0x40000
	s_addc_u32 s35, s31, 0
	s_add_i32 s72, s51, s36
	s_add_i32 s73, s72, 0x2000
	s_add_i32 s74, 0, 0x18000
	s_add_i32 s75, 0, 0x1c000
	s_add_u32 s26, s28, 0x40000
	s_addc_u32 s27, s29, 0
	s_add_i32 s66, s74, s36
	s_add_i32 s65, s66, 0x2000
	s_add_u32 s24, s30, 0x40080
	s_addc_u32 s25, s31, 0
	s_add_i32 s68, s75, s36
	s_add_i32 s67, s68, 0x2000
	s_cmp_lg_u32 s21, 12
	ds_read_b128 v[162:165], v219
	ds_read_b128 v[166:169], v219 offset:1024
	ds_read_b128 v[170:173], v219 offset:2048
	ds_read_b128 v[174:177], v219 offset:3072
	ds_read_b128 v[178:181], v219 offset:4096
	ds_read_b128 v[182:185], v219 offset:5120
	ds_read_b128 v[186:189], v219 offset:6144
	ds_read_b128 v[190:193], v219 offset:7168
	global_load_lds_dwordx4 v206, s[22:23]
	s_mov_b32 m0, s69
	s_nop 0
	global_load_lds_dwordx4 v208, s[22:23]
	s_waitcnt vmcnt(8)
	s_waitcnt lgkmcnt(0)
	s_barrier
	s_setprio 1
	s_waitcnt lgkmcnt(0)
	v_mfma_f32_16x16x32_bf16 v[126:129], v[130:133], v[162:165], 0
	v_mfma_f32_16x16x32_bf16 v[118:121], v[138:141], v[162:165], 0
	v_mfma_f32_16x16x32_bf16 v[110:113], v[130:133], v[170:173], 0
	v_mfma_f32_16x16x32_bf16 v[102:105], v[138:141], v[170:173], 0
	v_mfma_f32_16x16x32_bf16 v[94:97], v[130:133], v[178:181], 0
	v_mfma_f32_16x16x32_bf16 v[86:89], v[138:141], v[178:181], 0
	v_mfma_f32_16x16x32_bf16 v[78:81], v[130:133], v[186:189], 0
	v_mfma_f32_16x16x32_bf16 v[70:73], v[138:141], v[186:189], 0
	v_mfma_f32_16x16x32_bf16 v[126:129], v[134:137], v[166:169], v[126:129]
	v_mfma_f32_16x16x32_bf16 v[118:121], v[142:145], v[166:169], v[118:121]
	v_mfma_f32_16x16x32_bf16 v[110:113], v[134:137], v[174:177], v[110:113]
	v_mfma_f32_16x16x32_bf16 v[102:105], v[142:145], v[174:177], v[102:105]
	v_mfma_f32_16x16x32_bf16 v[94:97], v[134:137], v[182:185], v[94:97]
	v_mfma_f32_16x16x32_bf16 v[86:89], v[142:145], v[182:185], v[86:89]
	v_mfma_f32_16x16x32_bf16 v[78:81], v[134:137], v[190:193], v[78:81]
	v_mfma_f32_16x16x32_bf16 v[70:73], v[142:145], v[190:193], v[70:73]
	s_setprio 0
	s_setprio 1
	v_mfma_f32_16x16x32_bf16 v[122:125], v[146:149], v[162:165], 0
	v_mfma_f32_16x16x32_bf16 v[114:117], v[154:157], v[162:165], 0
	v_mfma_f32_16x16x32_bf16 v[106:109], v[146:149], v[170:173], 0
	v_mfma_f32_16x16x32_bf16 v[98:101], v[154:157], v[170:173], 0
	v_mfma_f32_16x16x32_bf16 v[90:93], v[146:149], v[178:181], 0
	v_mfma_f32_16x16x32_bf16 v[82:85], v[154:157], v[178:181], 0
	v_mfma_f32_16x16x32_bf16 v[74:77], v[146:149], v[186:189], 0
	v_mfma_f32_16x16x32_bf16 v[66:69], v[154:157], v[186:189], 0
	v_mfma_f32_16x16x32_bf16 v[122:125], v[150:153], v[166:169], v[122:125]
	v_mfma_f32_16x16x32_bf16 v[114:117], v[158:161], v[166:169], v[114:117]
	v_mfma_f32_16x16x32_bf16 v[106:109], v[150:153], v[174:177], v[106:109]
	v_mfma_f32_16x16x32_bf16 v[98:101], v[158:161], v[174:177], v[98:101]
	v_mfma_f32_16x16x32_bf16 v[90:93], v[150:153], v[182:185], v[90:93]
	v_mfma_f32_16x16x32_bf16 v[82:85], v[158:161], v[182:185], v[82:85]
	v_mfma_f32_16x16x32_bf16 v[74:77], v[150:153], v[190:193], v[74:77]
	v_mfma_f32_16x16x32_bf16 v[66:69], v[158:161], v[190:193], v[66:69]
	s_setprio 0
	s_barrier
; #define PG8_STAGE(bufoff, gbase, voff) do { _Pragma("unroll") for (int _i = 0; _i < 2; ++_i) \
;         __builtin_amdgcn_global_load_lds((const unsigned*)((const char*)(gbase) + (voff)[_i]), (LAS unsigned*)(lds + (bufoff) + ldsw + _i * 8192), 16, 0, 0); } while (0)
; #define PG8_LDA(dst, b, h) do { _Pragma("unroll") for (int m = 0; m < 4; ++m) _Pragma("unroll") for (int k = 0; k < 2; ++k) dst[m][k] = *(const LAS bf16x8*)(lds + PG8_SA(b, h) + aoff + m * 2048 + k * 1024); } while (0)
; #define PG8_MMA(ai, bj, At, Bt) do { __builtin_amdgcn_s_setprio(1); _Pragma("unroll") for (int m = 0; m < 4; ++m) _Pragma("unroll") for (int n = 0; n < 2; ++n) _Pragma("unroll") for (int k = 0; k < 2; ++k) \
;         acc[ai][bj][m][n] = __builtin_amdgcn_mfma_f32_16x16x32_bf16(Bt[n][k], At[m][k], acc[ai][bj][m][n], 0, 0, 0); __builtin_amdgcn_s_setprio(0); } while (0)
; #define PG8_WAIT_V(n) asm volatile("s_waitcnt vmcnt(" #n ")" ::: "memory")
; #define PG8_WAIT_L(n) asm volatile("s_waitcnt lgkmcnt(" #n ")" ::: "memory")
; #define PG8_BAR __builtin_amdgcn_s_barrier()
; #define PG8_SCHED __builtin_amdgcn_sched_barrier(0)
; template <class Epi, class Sched>
; __device__ __forceinline__ void gemm_phase(LAS unsigned char* lds, const int lda, const int ldb, const int K, const Sched& S, const Epi& E) {
;     ...
;             PG8_LDA(At, 0, 1); PG8_STAGE(PG8_SB(0, 0), b2, voffB); PG8_STAGE(PG8_SB(0, 1), b2 + hstepB, voffB); PG8_STAGE(PG8_SA(0, 0), a2, voffA);
;             PG8_WAIT_V(8); PG8_WAIT_L(0); PG8_BAR; PG8_MMA(1, 0, At, B0); PG8_MMA(1, 1, At, B1); PG8_BAR; PG8_SCHED;
	s_mov_b32 m0, s70
	ds_read_b128 v[162:165], v219 offset:16384
	ds_read_b128 v[166:169], v219 offset:17408
	ds_read_b128 v[170:173], v219 offset:18432
	ds_read_b128 v[174:177], v219 offset:19456
	ds_read_b128 v[178:181], v219 offset:20480
	ds_read_b128 v[182:185], v219 offset:21504
	ds_read_b128 v[186:189], v219 offset:22528
	ds_read_b128 v[190:193], v219 offset:23552
	global_load_lds_dwordx4 v200, s[30:31]
	s_mov_b32 m0, s71
	s_nop 0
	global_load_lds_dwordx4 v196, s[30:31]
	s_mov_b32 m0, s72
	s_nop 0
	global_load_lds_dwordx4 v200, s[34:35]
	s_mov_b32 m0, s73
	s_nop 0
	global_load_lds_dwordx4 v196, s[34:35]
	s_mov_b32 m0, s39
	s_nop 0
	global_load_lds_dwordx4 v202, s[28:29]
	s_mov_b32 m0, s40
	s_nop 0
	global_load_lds_dwordx4 v198, s[28:29]
	s_waitcnt vmcnt(8)
	s_waitcnt lgkmcnt(0)
	s_barrier
	s_setprio 1
	s_waitcnt lgkmcnt(0)
	v_mfma_f32_16x16x32_bf16 v[62:65], v[130:133], v[162:165], 0
	v_mfma_f32_16x16x32_bf16 v[54:57], v[138:141], v[162:165], 0
	v_mfma_f32_16x16x32_bf16 v[46:49], v[130:133], v[170:173], 0
	v_mfma_f32_16x16x32_bf16 v[38:41], v[138:141], v[170:173], 0
	v_mfma_f32_16x16x32_bf16 v[30:33], v[130:133], v[178:181], 0
	v_mfma_f32_16x16x32_bf16 v[22:25], v[138:141], v[178:181], 0
	v_mfma_f32_16x16x32_bf16 v[14:17], v[130:133], v[186:189], 0
	v_mfma_f32_16x16x32_bf16 v[6:9], v[138:141], v[186:189], 0
	v_mfma_f32_16x16x32_bf16 v[62:65], v[134:137], v[166:169], v[62:65]
	v_mfma_f32_16x16x32_bf16 v[54:57], v[142:145], v[166:169], v[54:57]
	v_mfma_f32_16x16x32_bf16 v[46:49], v[134:137], v[174:177], v[46:49]
	v_mfma_f32_16x16x32_bf16 v[38:41], v[142:145], v[174:177], v[38:41]
	v_mfma_f32_16x16x32_bf16 v[30:33], v[134:137], v[182:185], v[30:33]
	v_mfma_f32_16x16x32_bf16 v[22:25], v[142:145], v[182:185], v[22:25]
	v_mfma_f32_16x16x32_bf16 v[14:17], v[134:137], v[190:193], v[14:17]
	v_mfma_f32_16x16x32_bf16 v[6:9], v[142:145], v[190:193], v[6:9]
	s_setprio 0
	s_setprio 1
	v_mfma_f32_16x16x32_bf16 v[58:61], v[146:149], v[162:165], 0
	v_mfma_f32_16x16x32_bf16 v[50:53], v[154:157], v[162:165], 0
	v_mfma_f32_16x16x32_bf16 v[42:45], v[146:149], v[170:173], 0
	v_mfma_f32_16x16x32_bf16 v[34:37], v[154:157], v[170:173], 0
	v_mfma_f32_16x16x32_bf16 v[26:29], v[146:149], v[178:181], 0
	v_mfma_f32_16x16x32_bf16 v[18:21], v[154:157], v[178:181], 0
	v_mfma_f32_16x16x32_bf16 v[10:13], v[146:149], v[186:189], 0
	v_mfma_f32_16x16x32_bf16 v[2:5], v[154:157], v[186:189], 0
	v_mfma_f32_16x16x32_bf16 v[58:61], v[150:153], v[166:169], v[58:61]
	v_mfma_f32_16x16x32_bf16 v[50:53], v[158:161], v[166:169], v[50:53]
	v_mfma_f32_16x16x32_bf16 v[42:45], v[150:153], v[174:177], v[42:45]
	v_mfma_f32_16x16x32_bf16 v[34:37], v[158:161], v[174:177], v[34:37]
	v_mfma_f32_16x16x32_bf16 v[26:29], v[150:153], v[182:185], v[26:29]
	v_mfma_f32_16x16x32_bf16 v[18:21], v[158:161], v[182:185], v[18:21]
	v_mfma_f32_16x16x32_bf16 v[10:13], v[150:153], v[190:193], v[10:13]
	v_mfma_f32_16x16x32_bf16 v[2:5], v[158:161], v[190:193], v[2:5]
	s_setprio 0
	s_barrier
	s_branch .Lpeel6_join

; #define PG8_STAGE(bufoff, gbase, voff) do { _Pragma("unroll") for (int _i = 0; _i < 2; ++_i) \
;         __builtin_amdgcn_global_load_lds((const unsigned*)((const char*)(gbase) + (voff)[_i]), (LAS unsigned*)(lds + (bufoff) + ldsw + _i * 8192), 16, 0, 0); } while (0)
; #define PG8_LDA(dst, b, h) do { _Pragma("unroll") for (int m = 0; m < 4; ++m) _Pragma("unroll") for (int k = 0; k < 2; ++k) dst[m][k] = *(const LAS bf16x8*)(lds + PG8_SA(b, h) + aoff + m * 2048 + k * 1024); } while (0)
; #define PG8_LDB(dst, b, h) do { _Pragma("unroll") for (int n = 0; n < 2; ++n) _Pragma("unroll") for (int k = 0; k < 2; ++k) dst[n][k] = *(const LAS bf16x8*)(lds + PG8_SB(b, h) + boff + n * 2048 + k * 1024); } while (0)
; #define PG8_MMA(ai, bj, At, Bt) do { __builtin_amdgcn_s_setprio(1); _Pragma("unroll") for (int m = 0; m < 4; ++m) _Pragma("unroll") for (int n = 0; n < 2; ++n) _Pragma("unroll") for (int k = 0; k < 2; ++k) \
;         acc[ai][bj][m][n] = __builtin_amdgcn_mfma_f32_16x16x32_bf16(Bt[n][k], At[m][k], acc[ai][bj][m][n], 0, 0, 0); __builtin_amdgcn_s_setprio(0); } while (0)
; #define PG8_WAIT_V(n) asm volatile("s_waitcnt vmcnt(" #n ")" ::: "memory")
; #define PG8_WAIT_L(n) asm volatile("s_waitcnt lgkmcnt(" #n ")" ::: "memory")
; #define PG8_BAR __builtin_amdgcn_s_barrier()
; #define PG8_SCHED __builtin_amdgcn_sched_barrier(0)
; template <class Epi, class Sched>
; __device__ __forceinline__ void gemm_phase(LAS unsigned char* lds, const int lda, const int ldb, const int K, const Sched& S, const Epi& E) {
;     ...
;             PG8_LDB(B0, 1, 0); PG8_LDB(B1, 1, 1); PG8_SCHED; PG8_LDA(At, 1, 0); PG8_STAGE(PG8_SA(0, 1), a2 + hstepA, voffA);
;             PG8_WAIT_V(8); PG8_WAIT_L(0); PG8_BAR; PG8_MMA(0, 0, At, B0); PG8_MMA(0, 1, At, B1); PG8_BAR; PG8_SCHED;
;             PG8_LDA(At, 1, 1); PG8_STAGE(PG8_SB(1, 0), b3, voffB); PG8_STAGE(PG8_SB(1, 1), b3 + hstepB, voffB); PG8_STAGE(PG8_SA(1, 0), a3, voffA);
;             PG8_WAIT_V(8); PG8_WAIT_L(0); PG8_BAR;
;             if (last) E.pre(cur, wr, fr, rsv);
;     __device__ __forceinline__ void pre(const pg8::Unit& u, int wr, int fr, float (&rsv)[8]) const {
;         const float* p = ss + u.pm * 256 + wr * 64 + fr;
; #pragma unroll
;         for (int ai = 0; ai < 2; ++ai)
; #pragma unroll
;             for (int m = 0; m < 4; ++m) rsv[ai * 4 + m] = p[ai * 128 + m * 16];
;     }
.Lpeel6_join:
	v_add_u32_e32 v130, s74, v195
	v_add_u32_e32 v142, s75, v195
	ds_read_b128 v[146:149], v130
	ds_read_b128 v[150:153], v130 offset:1024
	ds_read_b128 v[154:157], v130 offset:2048
	ds_read_b128 v[158:161], v130 offset:3072
	ds_read_b128 v[130:133], v142
	ds_read_b128 v[134:137], v142 offset:1024
	ds_read_b128 v[138:141], v142 offset:2048
	ds_read_b128 v[142:145], v142 offset:3072
	s_mov_b32 m0, s41
	ds_read_b128 v[162:165], v219 offset:32768
	ds_read_b128 v[166:169], v219 offset:33792
	ds_read_b128 v[170:173], v219 offset:34816
	ds_read_b128 v[174:177], v219 offset:35840
	ds_read_b128 v[178:181], v219 offset:36864
	ds_read_b128 v[182:185], v219 offset:37888
	ds_read_b128 v[186:189], v219 offset:38912
	ds_read_b128 v[190:193], v219 offset:39936
	global_load_lds_dwordx4 v202, s[26:27]
	s_mov_b32 m0, s42
	s_nop 0
	global_load_lds_dwordx4 v198, s[26:27]
	s_waitcnt vmcnt(8)
	s_waitcnt lgkmcnt(0)
	s_barrier
	s_setprio 1
	s_waitcnt lgkmcnt(0)
	v_mfma_f32_16x16x32_bf16 v[126:129], v[146:149], v[162:165], v[126:129]
	v_mfma_f32_16x16x32_bf16 v[118:121], v[154:157], v[162:165], v[118:121]
	v_mfma_f32_16x16x32_bf16 v[110:113], v[146:149], v[170:173], v[110:113]
	v_mfma_f32_16x16x32_bf16 v[102:105], v[154:157], v[170:173], v[102:105]
	v_mfma_f32_16x16x32_bf16 v[94:97], v[146:149], v[178:181], v[94:97]
	v_mfma_f32_16x16x32_bf16 v[86:89], v[154:157], v[178:181], v[86:89]
	v_mfma_f32_16x16x32_bf16 v[78:81], v[146:149], v[186:189], v[78:81]
	v_mfma_f32_16x16x32_bf16 v[70:73], v[154:157], v[186:189], v[70:73]
	v_mfma_f32_16x16x32_bf16 v[126:129], v[150:153], v[166:169], v[126:129]
	v_mfma_f32_16x16x32_bf16 v[118:121], v[158:161], v[166:169], v[118:121]
	v_mfma_f32_16x16x32_bf16 v[110:113], v[150:153], v[174:177], v[110:113]
	v_mfma_f32_16x16x32_bf16 v[102:105], v[158:161], v[174:177], v[102:105]
	v_mfma_f32_16x16x32_bf16 v[94:97], v[150:153], v[182:185], v[94:97]
	v_mfma_f32_16x16x32_bf16 v[86:89], v[158:161], v[182:185], v[86:89]
	v_mfma_f32_16x16x32_bf16 v[78:81], v[150:153], v[190:193], v[78:81]
	v_mfma_f32_16x16x32_bf16 v[70:73], v[158:161], v[190:193], v[70:73]
	s_setprio 0
	s_setprio 1
	v_mfma_f32_16x16x32_bf16 v[122:125], v[130:133], v[162:165], v[122:125]
	v_mfma_f32_16x16x32_bf16 v[114:117], v[138:141], v[162:165], v[114:117]
	v_mfma_f32_16x16x32_bf16 v[106:109], v[130:133], v[170:173], v[106:109]
	v_mfma_f32_16x16x32_bf16 v[98:101], v[138:141], v[170:173], v[98:101]
	v_mfma_f32_16x16x32_bf16 v[90:93], v[130:133], v[178:181], v[90:93]
	v_mfma_f32_16x16x32_bf16 v[82:85], v[138:141], v[178:181], v[82:85]
	v_mfma_f32_16x16x32_bf16 v[74:77], v[130:133], v[186:189], v[74:77]
	v_mfma_f32_16x16x32_bf16 v[66:69], v[138:141], v[186:189], v[66:69]
	v_mfma_f32_16x16x32_bf16 v[122:125], v[134:137], v[166:169], v[122:125]
	v_mfma_f32_16x16x32_bf16 v[114:117], v[142:145], v[166:169], v[114:117]
	v_mfma_f32_16x16x32_bf16 v[106:109], v[134:137], v[174:177], v[106:109]
	v_mfma_f32_16x16x32_bf16 v[98:101], v[142:145], v[174:177], v[98:101]
	v_mfma_f32_16x16x32_bf16 v[90:93], v[134:137], v[182:185], v[90:93]
	v_mfma_f32_16x16x32_bf16 v[82:85], v[142:145], v[182:185], v[82:85]
	v_mfma_f32_16x16x32_bf16 v[74:77], v[134:137], v[190:193], v[74:77]
	v_mfma_f32_16x16x32_bf16 v[66:69], v[142:145], v[190:193], v[66:69]
	s_setprio 0
	s_barrier
	s_mov_b32 m0, s66
	ds_read_b128 v[186:189], v219 offset:49152
	ds_read_b128 v[190:193], v219 offset:50176
	ds_read_b128 v[178:181], v219 offset:51200
	ds_read_b128 v[182:185], v219 offset:52224
	ds_read_b128 v[170:173], v219 offset:53248
	ds_read_b128 v[174:177], v219 offset:54272
	ds_read_b128 v[162:165], v219 offset:55296
	ds_read_b128 v[166:169], v219 offset:56320
	global_load_lds_dwordx4 v230, s[30:31]
	s_mov_b32 m0, s65
	s_nop 0
	global_load_lds_dwordx4 v231, s[30:31]
	s_mov_b32 m0, s68
	s_nop 0
	global_load_lds_dwordx4 v200, s[24:25]
	s_mov_b32 m0, s67
	s_nop 0
	global_load_lds_dwordx4 v196, s[24:25]
	s_mov_b32 m0, s44
	s_nop 0
	global_load_lds_dwordx4 v232, s[28:29]
	s_mov_b32 m0, s45
	s_nop 0
	global_load_lds_dwordx4 v233, s[28:29]
	s_waitcnt vmcnt(8)
	s_waitcnt lgkmcnt(0)
	s_barrier
	s_cbranch_scc1 .LBB0_1053
	global_load_dword v228, v[214:215], off
	global_load_dword v227, v[214:215], off offset:64
	global_load_dword v226, v[214:215], off offset:128
	global_load_dword v225, v[214:215], off offset:192
	global_load_dword v224, v[214:215], off offset:512
	global_load_dword v223, v[214:215], off offset:576
	global_load_dword v222, v[214:215], off offset:640
	global_load_dword v221, v[214:215], off offset:704
	s_branch .LBB0_1053

; #define PG8_LDA(dst, b, h) do { _Pragma("unroll") for (int m = 0; m < 4; ++m) _Pragma("unroll") for (int k = 0; k < 2; ++k) dst[m][k] = *(const LAS bf16x8*)(lds + PG8_SA(b, h) + aoff + m * 2048 + k * 1024); } while (0)
; template <class Epi, class Sched>
; __device__ __forceinline__ void gemm_phase(LAS unsigned char* lds, const int lda, const int ldb, const int K, const Sched& S, const Epi& E) {
;     ...
;     Unit cur, nxt; int ui = 0;
;     if (!S.next(0, cur)) return;
;     f32x4 acc[2][2][4][2];
; #pragma unroll
;     for (int a = 0; a < 2; ++a)
; #pragma unroll
;         for (int b = 0; b < 2; ++b)
; #pragma unroll
;             for (int m = 0; m < 4; ++m)
; #pragma unroll
;                 for (int n = 0; n < 2; ++n) acc[a][b][m][n] = (f32x4){0.f, 0.f, 0.f, 0.f};
;     bf16x8 At[4][2], B0[2][2], B1[2][2];
;     float rsv[8];
; #pragma unroll
;     for (int i = 0; i < 8; ++i) rsv[i] = 0.f;
;     const char* cA = cur.A; const char* cB = cur.B;
;     PG8_STAGE(PG8_SB(0, 0), cB, voffB); PG8_STAGE(PG8_SB(0, 1), cB + hstepB, voffB); PG8_STAGE(PG8_SA(0, 0), cA, voffA); PG8_STAGE(PG8_SA(0, 1), cA + hstepA, voffA);
;     if (wr == 1) PG8_BAR;
;     PG8_WAIT_V(2); PG8_BAR;
;     PG8_STAGE(PG8_SB(1, 0), cB + kstep, voffB); PG8_STAGE(PG8_SA(1, 0), cA + kstep, voffA); PG8_STAGE(PG8_SB(1, 1), cB + hstepB + kstep, voffB);
;     PG8_WAIT_V(6); PG8_BAR;
;     for (;;) {
;         const bool has_next = S.next(ui + 1, nxt);
;         const char* nA = has_next ? nxt.A : cA; const char* nB = has_next ? nxt.B : cB;
;         for (int t = 0; t < nt; t += 2) {
;             const bool last = (t == nt - 2);
;             const char* a1 = cA + (size_t)(t + 1) * kstep;
;             const char* a2 = last ? nA : cA + (size_t)(t + 2) * kstep; const char* b2 = last ? nB : cB + (size_t)(t + 2) * kstep;
;             const char* a3 = a2 + kstep; const char* b3 = b2 + kstep;
;             PG8_LDB(B0, 0, 0); PG8_LDB(B1, 0, 1); PG8_SCHED; PG8_LDA(At, 0, 0); PG8_STAGE(PG8_SA(1, 1), a1 + hstepA, voffA);
;             PG8_WAIT_V(8); PG8_WAIT_L(0); PG8_BAR; PG8_MMA(0, 0, At, B0); PG8_MMA(0, 1, At, B1); PG8_BAR; PG8_SCHED;
;             PG8_LDA(At, 0, 1); PG8_STAGE(PG8_SB(0, 0), b2, voffB); PG8_STAGE(PG8_SB(0, 1), b2 + hstepB, voffB); PG8_STAGE(PG8_SA(0, 0), a2, voffA);
;             PG8_WAIT_V(8); PG8_WAIT_L(0); PG8_BAR; PG8_MMA(1, 0, At, B0); PG8_MMA(1, 1, At, B1); PG8_BAR; PG8_SCHED;
.LBB0_1135:
	s_add_u32 s14, s14, 0xb0080
	s_addc_u32 s15, s15, 0
	s_add_u32 s39, s16, 0x100
	s_addc_u32 s40, s17, 0
	s_mov_b32 s41, -2
	v_add_u32_e32 v214, 0x80, v132
	v_add_u32_e32 v215, 0x80, v128
	v_add_u32_e32 v216, 0x80, v134
	v_add_u32_e32 v217, 0x80, v130
	ds_read_b128 v[144:147], v151
	ds_read_b128 v[154:157], v151 offset:1024
	ds_read_b128 v[158:161], v151 offset:2048
	ds_read_b128 v[162:165], v151 offset:3072
	ds_read_b128 v[166:169], v152
	ds_read_b128 v[170:173], v152 offset:1024
	ds_read_b128 v[174:177], v152 offset:2048
	ds_read_b128 v[178:181], v152 offset:3072
	s_add_u32 s16, s14, 0xfff50080
	s_addc_u32 s17, s15, -1
	s_cmp_eq_u32 s41, 40
	s_cselect_b32 s19, s11, s17
	s_cselect_b32 s18, s10, s16
	s_cselect_b32 s17, s13, s40
	s_cselect_b32 s16, s12, s39
	s_add_i32 m0, s24, 0xc000
	ds_read_b128 v[182:185], v153
	ds_read_b128 v[186:189], v153 offset:1024
	ds_read_b128 v[190:193], v153 offset:2048
	ds_read_b128 v[194:197], v153 offset:3072
	ds_read_b128 v[198:201], v153 offset:4096
	ds_read_b128 v[202:205], v153 offset:5120
	ds_read_b128 v[206:209], v153 offset:6144
	ds_read_b128 v[210:213], v153 offset:7168
	global_load_lds_dwordx4 v136, s[14:15]
	s_add_i32 m0, s24, 0xe000
	s_nop 0
	global_load_lds_dwordx4 v138, s[14:15]
	s_waitcnt vmcnt(8)
	s_waitcnt lgkmcnt(0)
	s_barrier
	s_setprio 1
	s_waitcnt lgkmcnt(0)
	v_mfma_f32_16x16x32_bf16 v[124:127], v[144:147], v[182:185], 0
	v_mfma_f32_16x16x32_bf16 v[120:123], v[158:161], v[182:185], 0
	v_mfma_f32_16x16x32_bf16 v[112:115], v[144:147], v[190:193], 0
	v_mfma_f32_16x16x32_bf16 v[104:107], v[158:161], v[190:193], 0
	v_mfma_f32_16x16x32_bf16 v[96:99], v[144:147], v[198:201], 0
	v_mfma_f32_16x16x32_bf16 v[88:91], v[158:161], v[198:201], 0
	v_mfma_f32_16x16x32_bf16 v[80:83], v[144:147], v[206:209], 0
	v_mfma_f32_16x16x32_bf16 v[72:75], v[158:161], v[206:209], 0
	v_mfma_f32_16x16x32_bf16 v[124:127], v[154:157], v[186:189], v[124:127]
	v_mfma_f32_16x16x32_bf16 v[120:123], v[162:165], v[186:189], v[120:123]
	v_mfma_f32_16x16x32_bf16 v[112:115], v[154:157], v[194:197], v[112:115]
	v_mfma_f32_16x16x32_bf16 v[104:107], v[162:165], v[194:197], v[104:107]
	v_mfma_f32_16x16x32_bf16 v[96:99], v[154:157], v[202:205], v[96:99]
	v_mfma_f32_16x16x32_bf16 v[88:91], v[162:165], v[202:205], v[88:91]
	v_mfma_f32_16x16x32_bf16 v[80:83], v[154:157], v[210:213], v[80:83]
	v_mfma_f32_16x16x32_bf16 v[72:75], v[162:165], v[210:213], v[72:75]
	s_setprio 0
	s_setprio 1
	v_mfma_f32_16x16x32_bf16 v[116:119], v[166:169], v[182:185], 0
	v_mfma_f32_16x16x32_bf16 v[108:111], v[174:177], v[182:185], 0
	v_mfma_f32_16x16x32_bf16 v[100:103], v[166:169], v[190:193], 0
	v_mfma_f32_16x16x32_bf16 v[92:95], v[174:177], v[190:193], 0
	v_mfma_f32_16x16x32_bf16 v[84:87], v[166:169], v[198:201], 0
	v_mfma_f32_16x16x32_bf16 v[76:79], v[174:177], v[198:201], 0
	v_mfma_f32_16x16x32_bf16 v[68:71], v[166:169], v[206:209], 0
	v_mfma_f32_16x16x32_bf16 v[64:67], v[174:177], v[206:209], 0
	v_mfma_f32_16x16x32_bf16 v[116:119], v[170:173], v[186:189], v[116:119]
	v_mfma_f32_16x16x32_bf16 v[108:111], v[178:181], v[186:189], v[108:111]
	v_mfma_f32_16x16x32_bf16 v[100:103], v[170:173], v[194:197], v[100:103]
	v_mfma_f32_16x16x32_bf16 v[92:95], v[178:181], v[194:197], v[92:95]
	v_mfma_f32_16x16x32_bf16 v[84:87], v[170:173], v[202:205], v[84:87]
	v_mfma_f32_16x16x32_bf16 v[76:79], v[178:181], v[202:205], v[76:79]
	v_mfma_f32_16x16x32_bf16 v[68:71], v[170:173], v[210:213], v[68:71]
	v_mfma_f32_16x16x32_bf16 v[64:67], v[178:181], v[210:213], v[64:67]
	s_setprio 0
	s_barrier
	s_add_i32 s42, s33, s21
	s_mov_b32 m0, s42
	ds_read_b128 v[182:185], v153 offset:16384
	ds_read_b128 v[186:189], v153 offset:17408
	ds_read_b128 v[190:193], v153 offset:18432
	ds_read_b128 v[194:197], v153 offset:19456
	ds_read_b128 v[198:201], v153 offset:20480
	ds_read_b128 v[202:205], v153 offset:21504
	ds_read_b128 v[206:209], v153 offset:22528
	ds_read_b128 v[210:213], v153 offset:23552
	global_load_lds_dwordx4 v132, s[16:17]
	s_add_i32 m0, s42, 0x2000
	s_add_u32 s42, s16, 0xb0000
	s_mov_b64 s[98:99], s[16:17]
	s_addc_u32 s43, s17, 0
	s_add_i32 s44, s34, s21
	global_load_lds_dwordx4 v128, s[16:17]
	s_mov_b32 m0, s44
	s_mov_b64 s[100:101], s[18:19]
	global_load_lds_dwordx4 v132, s[42:43]
	s_add_i32 m0, s44, 0x2000
	s_nop 0
	global_load_lds_dwordx4 v128, s[42:43]
	s_mov_b32 m0, s24
	s_nop 0
	global_load_lds_dwordx4 v134, s[18:19]
	s_mov_b32 m0, s25
	s_nop 0
	global_load_lds_dwordx4 v130, s[18:19]
	s_waitcnt vmcnt(8)
	s_waitcnt lgkmcnt(0)
	s_barrier
	s_setprio 1
	s_waitcnt lgkmcnt(0)
	v_mfma_f32_16x16x32_bf16 v[60:63], v[144:147], v[182:185], 0
	v_mfma_f32_16x16x32_bf16 v[56:59], v[158:161], v[182:185], 0
	v_mfma_f32_16x16x32_bf16 v[48:51], v[144:147], v[190:193], 0
	v_mfma_f32_16x16x32_bf16 v[40:43], v[158:161], v[190:193], 0
	v_mfma_f32_16x16x32_bf16 v[32:35], v[144:147], v[198:201], 0
	v_mfma_f32_16x16x32_bf16 v[24:27], v[158:161], v[198:201], 0
	v_mfma_f32_16x16x32_bf16 v[16:19], v[144:147], v[206:209], 0
	v_mfma_f32_16x16x32_bf16 v[8:11], v[158:161], v[206:209], 0
	v_mfma_f32_16x16x32_bf16 v[60:63], v[154:157], v[186:189], v[60:63]
	v_mfma_f32_16x16x32_bf16 v[56:59], v[162:165], v[186:189], v[56:59]
	v_mfma_f32_16x16x32_bf16 v[48:51], v[154:157], v[194:197], v[48:51]
	v_mfma_f32_16x16x32_bf16 v[40:43], v[162:165], v[194:197], v[40:43]
	v_mfma_f32_16x16x32_bf16 v[32:35], v[154:157], v[202:205], v[32:35]
	v_mfma_f32_16x16x32_bf16 v[24:27], v[162:165], v[202:205], v[24:27]
	v_mfma_f32_16x16x32_bf16 v[16:19], v[154:157], v[210:213], v[16:19]
	v_mfma_f32_16x16x32_bf16 v[8:11], v[162:165], v[210:213], v[8:11]
	s_setprio 0
	s_setprio 1
	v_mfma_f32_16x16x32_bf16 v[52:55], v[166:169], v[182:185], 0
	v_mfma_f32_16x16x32_bf16 v[44:47], v[174:177], v[182:185], 0
	v_mfma_f32_16x16x32_bf16 v[36:39], v[166:169], v[190:193], 0
	v_mfma_f32_16x16x32_bf16 v[28:31], v[174:177], v[190:193], 0
	v_mfma_f32_16x16x32_bf16 v[20:23], v[166:169], v[198:201], 0
	v_mfma_f32_16x16x32_bf16 v[12:15], v[174:177], v[198:201], 0
	v_mfma_f32_16x16x32_bf16 v[4:7], v[166:169], v[206:209], 0
	v_mfma_f32_16x16x32_bf16 v[0:3], v[174:177], v[206:209], 0
	v_mfma_f32_16x16x32_bf16 v[52:55], v[170:173], v[186:189], v[52:55]
	v_mfma_f32_16x16x32_bf16 v[44:47], v[178:181], v[186:189], v[44:47]
	v_mfma_f32_16x16x32_bf16 v[36:39], v[170:173], v[194:197], v[36:39]
	v_mfma_f32_16x16x32_bf16 v[28:31], v[178:181], v[194:197], v[28:31]
	v_mfma_f32_16x16x32_bf16 v[20:23], v[170:173], v[202:205], v[20:23]
	v_mfma_f32_16x16x32_bf16 v[12:15], v[178:181], v[202:205], v[12:15]
	v_mfma_f32_16x16x32_bf16 v[4:7], v[170:173], v[210:213], v[4:7]
	v_mfma_f32_16x16x32_bf16 v[0:3], v[178:181], v[210:213], v[0:3]
	s_setprio 0
	s_barrier
	s_branch .Lpeel7_join

; #define PG8_STAGE(bufoff, gbase, voff) do { _Pragma("unroll") for (int _i = 0; _i < 2; ++_i) \
;         __builtin_amdgcn_global_load_lds((const unsigned*)((const char*)(gbase) + (voff)[_i]), (LAS unsigned*)(lds + (bufoff) + ldsw + _i * 8192), 16, 0, 0); } while (0)
; #define PG8_LDA(dst, b, h) do { _Pragma("unroll") for (int m = 0; m < 4; ++m) _Pragma("unroll") for (int k = 0; k < 2; ++k) dst[m][k] = *(const LAS bf16x8*)(lds + PG8_SA(b, h) + aoff + m * 2048 + k * 1024); } while (0)
; #define PG8_LDB(dst, b, h) do { _Pragma("unroll") for (int n = 0; n < 2; ++n) _Pragma("unroll") for (int k = 0; k < 2; ++k) dst[n][k] = *(const LAS bf16x8*)(lds + PG8_SB(b, h) + boff + n * 2048 + k * 1024); } while (0)
; #define PG8_MMA(ai, bj, At, Bt) do { __builtin_amdgcn_s_setprio(1); _Pragma("unroll") for (int m = 0; m < 4; ++m) _Pragma("unroll") for (int n = 0; n < 2; ++n) _Pragma("unroll") for (int k = 0; k < 2; ++k) \
;         acc[ai][bj][m][n] = __builtin_amdgcn_mfma_f32_16x16x32_bf16(Bt[n][k], At[m][k], acc[ai][bj][m][n], 0, 0, 0); __builtin_amdgcn_s_setprio(0); } while (0)
; #define PG8_WAIT_V(n) asm volatile("s_waitcnt vmcnt(" #n ")" ::: "memory")
; #define PG8_WAIT_L(n) asm volatile("s_waitcnt lgkmcnt(" #n ")" ::: "memory")
; #define PG8_BAR __builtin_amdgcn_s_barrier()
; #define PG8_SCHED __builtin_amdgcn_sched_barrier(0)
; template <class Epi, class Sched>
; __device__ __forceinline__ void gemm_phase(LAS unsigned char* lds, const int lda, const int ldb, const int K, const Sched& S, const Epi& E) {
;     ...
;             PG8_LDB(B0, 1, 0); PG8_LDB(B1, 1, 1); PG8_SCHED; PG8_LDA(At, 1, 0); PG8_STAGE(PG8_SA(0, 1), a2 + hstepA, voffA);
;             PG8_WAIT_V(8); PG8_WAIT_L(0); PG8_BAR; PG8_MMA(0, 0, At, B0); PG8_MMA(0, 1, At, B1); PG8_BAR; PG8_SCHED;
;             PG8_LDA(At, 1, 1); PG8_STAGE(PG8_SB(1, 0), b3, voffB); PG8_STAGE(PG8_SB(1, 1), b3 + hstepB, voffB); PG8_STAGE(PG8_SA(1, 0), a3, voffA);
;             PG8_WAIT_V(8); PG8_WAIT_L(0); PG8_BAR;
;             if (last) E.pre(cur, wr, fr, rsv);
;             PG8_MMA(1, 0, At, B0); PG8_MMA(1, 1, At, B1); PG8_BAR; PG8_SCHED;
;         }
;         if (wr == 0) PG8_BAR;
.Lpeel7_join:
	s_add_i32 s42, 0, 0x18000
	s_add_i32 s43, 0, 0x1c000
	v_add_u32_e32 v162, s42, v149
	v_add_u32_e32 v178, s43, v149
	ds_read_b128 v[144:147], v162
	ds_read_b128 v[154:157], v162 offset:1024
	ds_read_b128 v[158:161], v162 offset:2048
	ds_read_b128 v[162:165], v162 offset:3072
	ds_read_b128 v[166:169], v178
	ds_read_b128 v[170:173], v178 offset:1024
	ds_read_b128 v[174:177], v178 offset:2048
	ds_read_b128 v[178:181], v178 offset:3072
	s_add_u32 s18, s18, 0xb0000
	s_addc_u32 s19, s19, 0
	s_mov_b32 m0, s26
	ds_read_b128 v[182:185], v153 offset:32768
	ds_read_b128 v[186:189], v153 offset:33792
	ds_read_b128 v[190:193], v153 offset:34816
	ds_read_b128 v[194:197], v153 offset:35840
	ds_read_b128 v[198:201], v153 offset:36864
	ds_read_b128 v[202:205], v153 offset:37888
	ds_read_b128 v[206:209], v153 offset:38912
	ds_read_b128 v[210:213], v153 offset:39936
	global_load_lds_dwordx4 v134, s[18:19]
	s_mov_b32 m0, s27
	s_nop 0
	global_load_lds_dwordx4 v130, s[18:19]
	s_waitcnt vmcnt(8)
	s_waitcnt lgkmcnt(0)
	s_barrier
	s_setprio 1
	s_waitcnt lgkmcnt(0)
	v_mfma_f32_16x16x32_bf16 v[124:127], v[144:147], v[182:185], v[124:127]
	v_mfma_f32_16x16x32_bf16 v[120:123], v[158:161], v[182:185], v[120:123]
	v_mfma_f32_16x16x32_bf16 v[112:115], v[144:147], v[190:193], v[112:115]
	v_mfma_f32_16x16x32_bf16 v[104:107], v[158:161], v[190:193], v[104:107]
	v_mfma_f32_16x16x32_bf16 v[96:99], v[144:147], v[198:201], v[96:99]
	v_mfma_f32_16x16x32_bf16 v[88:91], v[158:161], v[198:201], v[88:91]
	v_mfma_f32_16x16x32_bf16 v[80:83], v[144:147], v[206:209], v[80:83]
	v_mfma_f32_16x16x32_bf16 v[72:75], v[158:161], v[206:209], v[72:75]
	v_mfma_f32_16x16x32_bf16 v[124:127], v[154:157], v[186:189], v[124:127]
	v_mfma_f32_16x16x32_bf16 v[120:123], v[162:165], v[186:189], v[120:123]
	v_mfma_f32_16x16x32_bf16 v[112:115], v[154:157], v[194:197], v[112:115]
	v_mfma_f32_16x16x32_bf16 v[104:107], v[162:165], v[194:197], v[104:107]
	v_mfma_f32_16x16x32_bf16 v[96:99], v[154:157], v[202:205], v[96:99]
	v_mfma_f32_16x16x32_bf16 v[88:91], v[162:165], v[202:205], v[88:91]
	v_mfma_f32_16x16x32_bf16 v[80:83], v[154:157], v[210:213], v[80:83]
	v_mfma_f32_16x16x32_bf16 v[72:75], v[162:165], v[210:213], v[72:75]
	s_setprio 0
	s_setprio 1
	v_mfma_f32_16x16x32_bf16 v[116:119], v[166:169], v[182:185], v[116:119]
	v_mfma_f32_16x16x32_bf16 v[108:111], v[174:177], v[182:185], v[108:111]
	v_mfma_f32_16x16x32_bf16 v[100:103], v[166:169], v[190:193], v[100:103]
	v_mfma_f32_16x16x32_bf16 v[92:95], v[174:177], v[190:193], v[92:95]
	v_mfma_f32_16x16x32_bf16 v[84:87], v[166:169], v[198:201], v[84:87]
	v_mfma_f32_16x16x32_bf16 v[76:79], v[174:177], v[198:201], v[76:79]
	v_mfma_f32_16x16x32_bf16 v[68:71], v[166:169], v[206:209], v[68:71]
	v_mfma_f32_16x16x32_bf16 v[64:67], v[174:177], v[206:209], v[64:67]
	v_mfma_f32_16x16x32_bf16 v[116:119], v[170:173], v[186:189], v[116:119]
	v_mfma_f32_16x16x32_bf16 v[108:111], v[178:181], v[186:189], v[108:111]
	v_mfma_f32_16x16x32_bf16 v[100:103], v[170:173], v[194:197], v[100:103]
	v_mfma_f32_16x16x32_bf16 v[92:95], v[178:181], v[194:197], v[92:95]
	v_mfma_f32_16x16x32_bf16 v[84:87], v[170:173], v[202:205], v[84:87]
	v_mfma_f32_16x16x32_bf16 v[76:79], v[178:181], v[202:205], v[76:79]
	v_mfma_f32_16x16x32_bf16 v[68:71], v[170:173], v[210:213], v[68:71]
	v_mfma_f32_16x16x32_bf16 v[64:67], v[178:181], v[210:213], v[64:67]
	s_setprio 0
	s_barrier
	s_add_i32 s18, s42, s21
	s_mov_b32 m0, s18
	ds_read_b128 v[182:185], v153 offset:49152
	ds_read_b128 v[186:189], v153 offset:50176
	ds_read_b128 v[190:193], v153 offset:51200
	ds_read_b128 v[194:197], v153 offset:52224
	ds_read_b128 v[198:201], v153 offset:53248
	ds_read_b128 v[202:205], v153 offset:54272
	ds_read_b128 v[206:209], v153 offset:55296
	ds_read_b128 v[210:213], v153 offset:56320
	global_load_lds_dwordx4 v214, s[16:17]
	s_add_i32 m0, s18, 0x2000
	s_add_u32 s16, s16, 0xb0080
	s_addc_u32 s17, s17, 0
	s_add_i32 s18, s43, s21
	global_load_lds_dwordx4 v215, s[98:99]
	s_mov_b32 m0, s18
	s_nop 0
	global_load_lds_dwordx4 v132, s[16:17]
	s_add_i32 m0, s18, 0x2000
	s_nop 0
	global_load_lds_dwordx4 v128, s[16:17]
	s_mov_b32 m0, s29
	s_nop 0
	global_load_lds_dwordx4 v216, s[100:101]
	s_mov_b32 m0, s30
	s_nop 0
	global_load_lds_dwordx4 v217, s[100:101]
	s_waitcnt vmcnt(8)
	s_waitcnt lgkmcnt(0)
	s_barrier
	s_setprio 1
	s_waitcnt lgkmcnt(0)
	v_mfma_f32_16x16x32_bf16 v[60:63], v[144:147], v[182:185], v[60:63]
	v_mfma_f32_16x16x32_bf16 v[56:59], v[158:161], v[182:185], v[56:59]
	v_mfma_f32_16x16x32_bf16 v[48:51], v[144:147], v[190:193], v[48:51]
	v_mfma_f32_16x16x32_bf16 v[40:43], v[158:161], v[190:193], v[40:43]
	v_mfma_f32_16x16x32_bf16 v[32:35], v[144:147], v[198:201], v[32:35]
	v_mfma_f32_16x16x32_bf16 v[24:27], v[158:161], v[198:201], v[24:27]
	v_mfma_f32_16x16x32_bf16 v[16:19], v[144:147], v[206:209], v[16:19]
	v_mfma_f32_16x16x32_bf16 v[8:11], v[158:161], v[206:209], v[8:11]
	v_mfma_f32_16x16x32_bf16 v[60:63], v[154:157], v[186:189], v[60:63]
	v_mfma_f32_16x16x32_bf16 v[56:59], v[162:165], v[186:189], v[56:59]
	v_mfma_f32_16x16x32_bf16 v[48:51], v[154:157], v[194:197], v[48:51]
	v_mfma_f32_16x16x32_bf16 v[40:43], v[162:165], v[194:197], v[40:43]
	v_mfma_f32_16x16x32_bf16 v[32:35], v[154:157], v[202:205], v[32:35]
	v_mfma_f32_16x16x32_bf16 v[24:27], v[162:165], v[202:205], v[24:27]
	v_mfma_f32_16x16x32_bf16 v[16:19], v[154:157], v[210:213], v[16:19]
	v_mfma_f32_16x16x32_bf16 v[8:11], v[162:165], v[210:213], v[8:11]
	s_setprio 0
	s_setprio 1
	v_mfma_f32_16x16x32_bf16 v[52:55], v[166:169], v[182:185], v[52:55]
	v_mfma_f32_16x16x32_bf16 v[44:47], v[174:177], v[182:185], v[44:47]
	v_mfma_f32_16x16x32_bf16 v[36:39], v[166:169], v[190:193], v[36:39]
	v_mfma_f32_16x16x32_bf16 v[28:31], v[174:177], v[190:193], v[28:31]
	v_mfma_f32_16x16x32_bf16 v[20:23], v[166:169], v[198:201], v[20:23]
	v_mfma_f32_16x16x32_bf16 v[12:15], v[174:177], v[198:201], v[12:15]
	v_mfma_f32_16x16x32_bf16 v[4:7], v[166:169], v[206:209], v[4:7]
	v_mfma_f32_16x16x32_bf16 v[0:3], v[174:177], v[206:209], v[0:3]
	v_mfma_f32_16x16x32_bf16 v[52:55], v[170:173], v[186:189], v[52:55]
	v_mfma_f32_16x16x32_bf16 v[44:47], v[178:181], v[186:189], v[44:47]
	v_mfma_f32_16x16x32_bf16 v[36:39], v[170:173], v[194:197], v[36:39]
	v_mfma_f32_16x16x32_bf16 v[28:31], v[178:181], v[194:197], v[28:31]
	v_mfma_f32_16x16x32_bf16 v[20:23], v[170:173], v[202:205], v[20:23]
	v_mfma_f32_16x16x32_bf16 v[12:15], v[178:181], v[202:205], v[12:15]
	v_mfma_f32_16x16x32_bf16 v[4:7], v[170:173], v[210:213], v[4:7]
	v_mfma_f32_16x16x32_bf16 v[0:3], v[178:181], v[210:213], v[0:3]
	s_setprio 0
	s_barrier
	s_add_i32 s41, s41, 2
	s_add_u32 s14, s14, 0x100
	s_addc_u32 s15, s15, 0
	s_add_u32 s39, s39, 0x100
	s_addc_u32 s40, s40, 0
	s_cmp_gt_u32 s41, 41
	s_cbranch_scc0 .LBB0_1136
	s_and_b64 vcc, exec, s[8:9]
	s_cbranch_vccz .LBB0_1139
	s_barrier
